# diff attention main loop trims: row-sum cross-half combine deferred to after the loop, redundant max canonicalisation / post-inline-asm nops removed, rescale test moved off the common path, paired LDS
# speedup vs baseline: 1.0263x; 1.0107x over previous
; __device__ __forceinline__ float max3f(float a, float b, float c) { float r; asm("v_max3_f32 %0, %1, %2, %3" : "=v"(r) : "v"(a), "v"(b), "v"(c)); return r; }
; #define SLOAD(i, k0) do { sr_[i].vs0 = ld8(&Vg[(long)((k0) + sr) * LDP + sc]); sr_[i].vs1 = ld8(&Vg[(long)((k0) + 32 + sr) * LDP + sc]); \
;     sr_[i].ks0 = ld8(&Kg[(long)((k0) + sr) * LDP + sc]); sr_[i].ks1 = ld8(&Kg[(long)((k0) + 32 + sr) * LDP + sc]); } while (0)
; #define SWRITE(off, i) do { *(bf16x8*)(V_lds + (off) + vst0) = sr_[i].vs0;          \
;     *(bf16x8*)(V_lds + (off) + vst1) = sr_[i].vs1; int kc = sc * 2;               \
;     *(bf16x8*)(K_lds + (off) + KSWZ(sr, kc)) = sr_[i].ks0;                       \
;     *(bf16x8*)(K_lds + (off) + KSWZ(32 + sr, kc)) = sr_[i].ks1; } while (0)
; #define SWAIT() asm volatile("s_waitcnt vmcnt(0)" ::: "memory")
; template <bool FIRST> __device__ __forceinline__ void partialSM2(f32x16& p0, f32x16& p1, float& m_ref, f32x16& negm, float& alpha) {
;   float pmax = max3f(p0[0], p0[1], p1[0]), pmb = max3f(p0[2], p0[3], p1[1]);
;   pmax = max3f(pmax, p1[2], p1[3]);
; #pragma unroll
;   for (int r = 4; r < 16; r += 4) { pmax = max3f(pmax, p0[r], p0[r + 1]); pmb = max3f(pmb, p0[r + 2], p0[r + 3]); pmax = max3f(pmax, p1[r], p1[r + 1]); pmb = max3f(pmb, p1[r + 2], p1[r + 3]); }
;   pmax = max3f(pmax, pmb, pmb);
;   { auto rr = __builtin_amdgcn_permlane32_swap(__float_as_uint(pmax), __float_as_uint(pmax), false, false);
;     pmax = fmaxf(__uint_as_float(rr[0]), __uint_as_float(rr[1])); }
;   alpha = 1.f;
;   if (FIRST || !__builtin_expect(__all(pmax <= THR), 1)) {
;     const float dl = FIRST ? pmax : fmaxf(pmax, 0.f); m_ref += dl; if (!FIRST) alpha = __builtin_amdgcn_exp2f(-dl);
; #pragma unroll
;     for (int r = 0; r < 16; ++r) { p0[r] -= dl; p1[r] -= dl; negm[r] -= dl; }
;   }
; #pragma unroll
;   for (int r = 0; r < 16; ++r) p0[r] = __builtin_amdgcn_exp2f(p0[r]);
; template <int MODE, int ORD> ...
;     ...
;   SETBE(0); qkt<ND0>(pA0, pA1, K_lds, qr, r32, hi, cboff, negm); BIAS(pA0, pA1, 0); partialSM2<MODE == 0>(pA0, pA1, m_reg, negm, alA);
;   SLOAD(SO, KVBLK);
;   SWAIT(); SWRITE(SLOT, SO); __syncthreads();
;   int op = 0, oc = SLOT, on = 2 * SLOT;
.LBB0_162:
	v_and_b32_e32 v1, 63, v40
	v_lshlrev_b32_e32 v35, 4, v1
	v_lshlrev_b32_e32 v34, 3, v1
	v_and_b32_e32 v35, 0xc0, v35
	v_lshlrev_b32_e32 v36, 1, v1
	v_and_or_b32 v35, v34, 24, v35
	v_and_b32_e32 v36, 32, v36
	v_and_b32_e32 v34, 0x100, v34
	s_cmp_lg_u32 0, -1
	v_or3_b32 v34, v35, v36, v34
	s_cselect_b32 s34, 0, 0
	v_add_u32_e32 v199, s34, v34
	v_max3_f32 v34, v18, v19, v2
	v_max3_f32 v35, v20, v21, v3
	v_cndmask_b32_e64 v214, 0, v46, s[0:1]
	v_max3_f32 v34, v34, v4, v5
	v_max3_f32 v35, v35, v24, v25
	s_and_b32 s0, s63, 0x3fffffc0
	v_max3_f32 v34, v34, v22, v23
	v_max3_f32 v35, v35, v8, v9
	s_lshl_b32 s0, s0, 2
	v_max3_f32 v34, v34, v6, v7
	v_max3_f32 v35, v35, v28, v29
	v_add_u32_e32 v36, 0x60, v38
	v_max3_f32 v34, v34, v26, v27
	s_add_i32 s49, s0, 0
	v_max3_f32 v58, v34, v10, v11
	v_add_u32_e32 v34, 64, v38
	v_max3_f32 v59, v35, v12, v13
	v_mad_i64_i32 v[34:35], s[0:1], v34, s73, 0
	v_mad_i64_i32 v[36:37], s[0:1], v36, s73, 0
	v_or_b32_e32 v34, v34, v41
	v_or_b32_e32 v36, v36, v41
	v_lshlrev_b64 v[50:51], 1, v[34:35]
	v_lshlrev_b64 v[52:53], 1, v[36:37]
	v_lshl_add_u64 v[34:35], s[42:43], 0, v[50:51]
	v_lshl_add_u64 v[46:47], s[42:43], 0, v[52:53]
	v_lshl_add_u64 v[50:51], s[18:19], 0, v[50:51]
	v_lshl_add_u64 v[54:55], s[18:19], 0, v[52:53]
	global_load_dwordx4 v[34:37], v[34:35], off
	s_nop 0
	global_load_dwordx4 v[46:49], v[46:47], off
	s_nop 0
	global_load_dwordx4 v[50:53], v[50:51], off offset:2048
	s_nop 0
	global_load_dwordx4 v[54:57], v[54:55], off offset:2048
	v_max3_f32 v41, v58, v30, v31
	v_max3_f32 v58, v59, v32, v33
	s_add_i32 s68, s68, s79
	v_max3_f32 v41, v41, v14, v15
	v_max3_f32 v58, v58, v16, v17
	v_ashrrev_i32_e32 v39, 31, v38
	v_max3_f32 v41, v41, v58, v58
	v_cmp_gt_u32_e64 s[0:1], 32, v1
	v_mov_b32_e32 v58, v41
	s_nop 1
	v_permlane32_swap_b32_e32 v41, v58
	v_max_f32_e32 v58, v58, v58
	v_max_f32_e32 v41, v41, v41
	v_max_f32_e32 v41, v41, v58
	v_sub_f32_e32 v64, v0, v41
	v_add_u32_e32 v0, s68, v184
	v_sub_f32_e32 v81, v3, v41
	v_sub_f32_e32 v80, v2, v41
	v_sub_u32_e32 v202, v197, v0
	v_lshl_add_u64 v[0:1], s[10:11], 0, v[38:39]
	v_mov_b32_e32 v2, s78
	v_mov_b32_e32 v3, v205
	v_mad_u64_u32 v[2:3], s[10:11], v0, s53, v[2:3]
	v_mov_b32_e32 v0, v3
	v_sub_f32_e32 v18, v18, v41
	v_sub_f32_e32 v19, v19, v41
	v_sub_f32_e32 v20, v20, v41
	v_sub_f32_e32 v21, v21, v41
	v_sub_f32_e32 v22, v22, v41
	v_sub_f32_e32 v23, v23, v41
	v_sub_f32_e32 v24, v24, v41
	v_sub_f32_e32 v25, v25, v41
	v_sub_f32_e32 v26, v26, v41
	v_sub_f32_e32 v27, v27, v41
	v_sub_f32_e32 v28, v28, v41
	v_sub_f32_e32 v29, v29, v41
	v_sub_f32_e32 v30, v30, v41
	v_sub_f32_e32 v31, v31, v41
	v_sub_f32_e32 v32, v32, v41
	v_sub_f32_e32 v33, v33, v41
	v_mad_u64_u32 v[0:1], s[10:11], v1, s53, v[0:1]
	v_exp_f32_e32 v173, v18
	v_exp_f32_e32 v175, v19
	v_exp_f32_e32 v171, v20
	v_exp_f32_e32 v174, v21
	v_exp_f32_e32 v169, v22
	v_exp_f32_e32 v172, v23
	v_exp_f32_e32 v168, v24
	v_exp_f32_e32 v170, v25
	v_exp_f32_e32 v165, v26
	v_exp_f32_e32 v167, v27
	v_exp_f32_e32 v163, v28
	v_exp_f32_e32 v166, v29
	v_exp_f32_e32 v161, v30
	v_exp_f32_e32 v164, v31
	v_exp_f32_e32 v160, v32
	v_exp_f32_e32 v162, v33
	v_and_b32_e32 v1, 15, v40
	v_readlane_b32 s10, v255, 31
	v_sub_f32_e32 v93, v15, v41
	v_sub_f32_e32 v92, v14, v41
	s_waitcnt vmcnt(0)
	v_lshl_or_b32 v2, v1, 4, v2
	v_mov_b32_e32 v3, v0
	v_readlane_b32 s11, v255, 32
	v_mov_b32_e32 v14, v205
	v_mov_b32_e32 v15, v205
	s_add_i32 s49, s49, 0x18000
	v_sub_f32_e32 v95, v17, v41
	v_sub_f32_e32 v94, v16, v41
	v_sub_f32_e32 v91, v13, v41
	v_sub_f32_e32 v90, v12, v41
	v_sub_f32_e32 v89, v11, v41
	v_sub_f32_e32 v88, v10, v41
	v_sub_f32_e32 v87, v9, v41
	v_sub_f32_e32 v86, v8, v41
	v_sub_f32_e32 v85, v7, v41
	v_sub_f32_e32 v84, v6, v41
	v_sub_f32_e32 v83, v5, v41
	v_sub_f32_e32 v82, v4, v41
	s_waitcnt vmcnt(3)
	ds_write_b128 v44, v[34:37] offset:32768
	s_waitcnt vmcnt(2)
	ds_write_b128 v45, v[46:49] offset:32768
	s_waitcnt vmcnt(1)
	ds_write_b128 v42, v[50:53] offset:49152
	s_waitcnt vmcnt(0)
	ds_write_b128 v43, v[54:57] offset:49152
	v_lshl_add_u64 v[176:177], s[10:11], 0, v[2:3]
	v_and_b32_e32 v240, 63, v244
	s_lshl_b32 s100, s62, 2
	s_and_b32 s101, s62, 1
	s_lshl_b32 s101, s101, 3
	v_lshrrev_b32_e32 v241, 4, v240
	v_or_b32_e32 v242, s101, v241
	v_and_b32_e32 v243, 15, v240
	v_xor_b32_e32 v242, v243, v242
	v_add_u32_e32 v245, s100, v241
	v_mul_u32_u24_e32 v245, 0x2400, v245
	v_lshl_add_u32 v234, v242, 4, v245
	v_xor_b32_e32 v242, 4, v242
	v_add_u32_e32 v245, 0x8c00, v245
	v_lshl_add_u32 v235, v242, 4, v245
	v_bfe_u32 v241, v240, 2, 3
	s_lshl_b32 s101, s62, 3
	v_or_b32_e32 v241, s101, v241
	v_mov_b32_e32 v242, v241
	v_subrev_u32_e32 v242, s100, v242
	v_mul_u32_u24_e32 v242, 0x2400, v242
	v_lshrrev_b32_e32 v243, 5, v240
	v_lshlrev_b32_e32 v243, 6, v243
	v_and_b32_e32 v245, 3, v240
	v_lshl_add_u32 v243, v245, 4, v243
	v_add_u32_e32 v236, v242, v243
	v_add_u32_e32 v236, 0x800, v236
	v_subrev_u32_e32 v237, 0x380, v236
	v_readfirstlane_b32 s100, v176
	v_readfirstlane_b32 s101, v177
	v_mov_b32_e32 v0, v205
	v_mov_b32_e32 v1, v205
	v_mov_b32_e32 v2, v205
	v_mov_b32_e32 v3, v205
	v_mov_b32_e32 v4, v205
	v_mov_b32_e32 v5, v205
	v_mov_b32_e32 v6, v205
	v_mov_b32_e32 v7, v205
	v_mov_b32_e32 v8, v205
	v_mov_b32_e32 v9, v205
	v_mov_b32_e32 v10, v205
	v_mov_b32_e32 v11, v205
	v_mov_b32_e32 v12, v205
	v_mov_b32_e32 v13, v205
	v_mov_b64_e32 v[62:63], v[14:15]
	v_mov_b64_e32 v[46:47], v[14:15]
	v_mov_b64_e32 v[30:31], v[14:15]
	s_mov_b32 s56, 0
	s_mov_b32 s57, 2
	v_mov_b32_e32 v65, v64
	v_mov_b32_e32 v66, v64
	v_mov_b32_e32 v67, v64
	v_mov_b32_e32 v68, v64
	v_mov_b32_e32 v69, v64
	v_mov_b32_e32 v70, v64
	v_mov_b32_e32 v71, v64
	v_mov_b32_e32 v72, v64
	v_mov_b32_e32 v73, v64
	v_mov_b32_e32 v74, v64
	v_mov_b32_e32 v75, v64
	v_mov_b32_e32 v76, v64
	v_mov_b32_e32 v77, v64
	v_mov_b32_e32 v78, v64
	v_mov_b32_e32 v79, v64
	s_add_i32 s19, s92, 0x9f
	v_lshl_add_u32 v186, v184, 2, s49
	s_sub_i32 s42, 0, s68
	v_mov_b32_e32 v187, 0
	v_mov_b32_e32 v203, 1.0
	s_mov_b32 s18, 0x10000
	s_mov_b32 s43, 0x8000
	v_mov_b64_e32 v[60:61], v[12:13]
	v_mov_b64_e32 v[58:59], v[10:11]
	v_mov_b64_e32 v[56:57], v[8:9]
	v_mov_b64_e32 v[54:55], v[6:7]
	v_mov_b64_e32 v[52:53], v[4:5]
	v_mov_b64_e32 v[50:51], v[2:3]
	v_mov_b64_e32 v[48:49], v[0:1]
	v_mov_b64_e32 v[44:45], v[12:13]
	v_mov_b64_e32 v[42:43], v[10:11]
	v_mov_b64_e32 v[40:41], v[8:9]
	v_mov_b64_e32 v[38:39], v[6:7]
	v_mov_b64_e32 v[36:37], v[4:5]
	v_mov_b64_e32 v[34:35], v[2:3]
	v_mov_b64_e32 v[32:33], v[0:1]
	v_mov_b64_e32 v[28:29], v[12:13]
	v_mov_b64_e32 v[26:27], v[10:11]
	v_mov_b64_e32 v[24:25], v[8:9]
	v_mov_b64_e32 v[22:23], v[6:7]
	v_mov_b64_e32 v[20:21], v[4:5]
	v_mov_b64_e32 v[18:19], v[2:3]
	v_mov_b64_e32 v[16:17], v[0:1]
	s_mov_b32 s10, 0
	s_waitcnt lgkmcnt(0)
	s_barrier
; template <int MODE, int ORD> ...
;     ...
;   float bL, bR, be_cur = 0.f; f32x16 negm;
; #pragma unroll
;   for (int r = 0; r < 16; ++r) negm[r] = -m_reg;
.LBB0_163:
	s_mov_b32 s68, s43
	s_mov_b32 s43, s10
	s_lshl_b32 m0, s62, 11
	s_add_i32 m0, m0, s18
	s_nop 0
	global_load_lds_dwordx4 v236, s[100:101]
	global_load_lds_dwordx4 v237, s[100:101] offset:1024
	s_addk_i32 m0, 0x4000
	s_nop 0
	global_load_lds_dwordx4 v234, s[100:101]
	global_load_lds_dwordx4 v235, s[100:101] offset:1024
	s_add_u32 s100, s100, 0x90000
	s_addc_u32 s101, s101, 0
	s_add_i32 s78, s42, s56
	s_add_i32 s34, s56, 64
	s_add_i32 s35, s78, 0x7f
	s_cmpk_gt_i32 s35, 0xff80
	s_cselect_b64 s[10:11], -1, 0
	s_cmp_lt_u32 s34, s19
	s_cselect_b64 s[80:81], -1, 0
	s_and_b64 s[10:11], s[10:11], s[80:81]
	s_cmpk_lt_i32 s35, 0xff81
	s_cselect_b64 vcc, -1, 0
	v_cndmask_b32_e32 v96, v200, v195, vcc
	v_cndmask_b32_e64 v215, v96, 0, s[10:11]
	v_cmp_eq_f32_e32 vcc, v215, v214
	s_cbranch_vccnz .LBB0_165
	v_sub_f32_e32 v96, v215, v214
	v_pk_add_f32 v[78:79], v[78:79], v[96:97] op_sel_hi:[1,0]
	v_pk_add_f32 v[76:77], v[76:77], v[96:97] op_sel_hi:[1,0]
	v_pk_add_f32 v[74:75], v[74:75], v[96:97] op_sel_hi:[1,0]
	v_pk_add_f32 v[72:73], v[72:73], v[96:97] op_sel_hi:[1,0]
	v_pk_add_f32 v[70:71], v[70:71], v[96:97] op_sel_hi:[1,0]
	v_pk_add_f32 v[68:69], v[68:69], v[96:97] op_sel_hi:[1,0]
	v_pk_add_f32 v[66:67], v[66:67], v[96:97] op_sel_hi:[1,0]
	v_pk_add_f32 v[64:65], v[64:65], v[96:97] op_sel_hi:[1,0]
	s_branch .LBB0_166

; __device__ __forceinline__ void finishSM(f32x16& p0, f32x16& p1, float alpha, float& l_reg, bf16x8& pa0, bf16x8& pa1, bf16x8& pa2, bf16x8& pa3) {
; #pragma unroll
;   for (int r = 0; r < 16; ++r) p1[r] = __builtin_amdgcn_exp2f(p1[r]);
;   float ps = 0;
; #pragma unroll
;   for (int r = 0; r < 16; ++r) ps += p0[r];
; #pragma unroll
;   for (int r = 0; r < 16; ++r) ps += p1[r];
;   { auto rr = __builtin_amdgcn_permlane32_swap(__float_as_uint(ps), __float_as_uint(ps), false, false);
;     ps = __uint_as_float(rr[0]) + __uint_as_float(rr[1]); }
;   l_reg = l_reg * alpha + ps;
;     ...
;   PK4(p0, 0, pa0); PK4(p0, 8, pa1); PK4(p1, 0, pa2); PK4(p1, 8, pa3);
;     ...
; }
.LBB0_166:
	s_add_i32 s34, s68, 0
	v_add_u32_e32 v96, s34, v188
	ds_read_b128 v[210:213], v96 offset:24576
	ds_read_b128 v[96:99], v96 offset:16384
	v_add_u32_e32 v201, s34, v196
	v_exp_f32_e32 v206, v81
	v_exp_f32_e32 v207, v82
	v_exp_f32_e32 v208, v83
	s_waitcnt lgkmcnt(0)
	v_mfma_f32_32x32x16_bf16 v[112:127], v[96:99], v[128:131], v[64:79]
	v_exp_f32_e32 v209, v84
	v_exp_f32_e32 v87, v87
	v_exp_f32_e32 v214, v88
	v_exp_f32_e32 v220, v93
	v_exp_f32_e32 v221, v94
	v_exp_f32_e32 v95, v95
	v_mfma_f32_32x32x16_bf16 v[96:111], v[210:213], v[128:131], v[64:79]
	ds_read_b128 v[210:213], v201 offset:24576
	ds_read_b128 v[216:219], v201 offset:16384
	v_add_u32_e32 v201, s34, v190
	s_waitcnt lgkmcnt(0)
	v_mfma_f32_32x32x16_bf16 v[112:127], v[216:219], v[132:135], v[112:127]
	v_mfma_f32_32x32x16_bf16 v[96:111], v[210:213], v[132:135], v[96:111]
	ds_read_b128 v[210:213], v201 offset:24576
	ds_read_b128 v[216:219], v201 offset:16384
	v_add_u32_e32 v201, s34, v189
	s_waitcnt lgkmcnt(0)
	v_mfma_f32_32x32x16_bf16 v[112:127], v[216:219], v[136:139], v[112:127]
	v_mfma_f32_32x32x16_bf16 v[96:111], v[210:213], v[136:139], v[96:111]
	ds_read_b128 v[210:213], v201 offset:24576
	ds_read_b128 v[216:219], v201 offset:16384
	v_exp_f32_e32 v201, v80
	v_pk_add_f32 v[144:145], v[160:161], v[162:163]
	v_pk_add_f32 v[144:145], v[144:145], v[164:165]
	v_pk_add_f32 v[144:145], v[144:145], v[166:167]
	v_pk_add_f32 v[144:145], v[144:145], v[168:169]
	v_pk_add_f32 v[144:145], v[144:145], v[170:171]
	v_pk_add_f32 v[144:145], v[144:145], v[172:173]
	v_pk_add_f32 v[144:145], v[144:145], v[174:175]
	v_pk_add_f32 v[144:145], v[144:145], v[206:207]
	v_pk_add_f32 v[144:145], v[144:145], v[208:209]
	v_pk_add_f32 v[144:145], v[144:145], v[220:221]
	v_add_f32_e32 v80, v87, v214
	v_add_f32_e32 v80, v95, v80
	s_waitcnt lgkmcnt(1)
	v_mfma_f32_32x32x16_bf16 v[96:111], v[210:213], v[140:143], v[96:111]
	v_exp_f32_e32 v212, v85
	v_add_f32_e32 v80, v201, v80
	v_exp_f32_e32 v213, v86
	s_waitcnt lgkmcnt(0)
	v_mfma_f32_32x32x16_bf16 v[112:127], v[216:219], v[140:143], v[112:127]
	v_exp_f32_e32 v216, v89
	v_exp_f32_e32 v217, v90
	v_exp_f32_e32 v218, v91
	v_exp_f32_e32 v219, v92
	v_pk_add_f32 v[144:145], v[144:145], v[212:213]
	v_pk_add_f32 v[144:145], v[144:145], v[216:217]
	v_pk_add_f32 v[144:145], v[144:145], v[218:219]
	v_add_f32_e32 v80, v144, v80
	v_add_f32_e32 v210, v145, v80
	v_cvt_pk_bf16_f32 v80, v173, v175
	v_cvt_pk_bf16_f32 v81, v171, v174
	v_cvt_pk_bf16_f32 v82, v169, v172
	v_cvt_pk_bf16_f32 v83, v168, v170
	v_cvt_pk_bf16_f32 v88, v165, v167
	v_cvt_pk_bf16_f32 v89, v163, v166
	v_cvt_pk_bf16_f32 v90, v161, v164
	v_cvt_pk_bf16_f32 v91, v160, v162
	v_cvt_pk_bf16_f32 v84, v201, v206
	v_cvt_pk_bf16_f32 v85, v207, v208
	v_cvt_pk_bf16_f32 v86, v209, v212
	v_cvt_pk_bf16_f32 v87, v213, v87
	v_cvt_pk_bf16_f32 v92, v214, v216
	v_cvt_pk_bf16_f32 v93, v217, v218
	v_cvt_pk_bf16_f32 v94, v219, v220
	v_cvt_pk_bf16_f32 v95, v221, v95
	s_andn2_b64 vcc, exec, s[10:11]
	v_add_u32_e32 v212, s56, v202
	s_cbranch_vccnz .LBB0_168
	v_add_u32_e32 v160, 0xc0, v212
	v_med3_i32 v161, v160, 0, v249
	v_med3_i32 v160, v160, s75, v250
	v_lshl_add_u32 v162, v160, 2, s69
	v_add_u32_e32 v160, 0xc1, v212
	v_med3_i32 v163, v160, 0, v249
	v_med3_i32 v160, v160, s75, v250
	v_lshl_add_u32 v164, v160, 2, s69
	v_add_u32_e32 v160, 0xc2, v212
	v_med3_i32 v165, v160, 0, v249
	v_med3_i32 v160, v160, s75, v250
	v_lshl_add_u32 v166, v160, 2, s69
	v_add_u32_e32 v160, 0xc3, v212
	v_med3_i32 v167, v160, 0, v249
	v_med3_i32 v160, v160, s75, v250
	v_lshl_add_u32 v161, v161, 2, s69
	v_lshl_add_u32 v163, v163, 2, s69
	v_lshl_add_u32 v165, v165, 2, s69
	v_lshl_add_u32 v167, v167, 2, s69
	v_lshl_add_u32 v168, v160, 2, s69
	ds_read_b32 v160, v161
	ds_read_b32 v162, v162 offset:128
	ds_read_b32 v161, v163
	ds_read_b32 v163, v164 offset:128
	ds_read_b32 v164, v165
	ds_read_b32 v166, v166 offset:128
	ds_read_b32 v165, v167
	ds_read_b32 v167, v168 offset:128
	v_add_u32_e32 v168, 0xc8, v212
	v_med3_i32 v169, v168, 0, v249
	v_med3_i32 v168, v168, s75, v250
	v_lshl_add_u32 v170, v168, 2, s69
	v_add_u32_e32 v168, 0xc9, v212
	v_med3_i32 v171, v168, 0, v249
	v_med3_i32 v168, v168, s75, v250
	v_lshl_add_u32 v172, v168, 2, s69
	v_add_u32_e32 v168, 0xca, v212
	v_med3_i32 v173, v168, 0, v249
	v_med3_i32 v168, v168, s75, v250
	v_add_u32_e32 v207, 0xd1, v212
	v_lshl_add_u32 v174, v168, 2, s69
	v_add_u32_e32 v168, 0xcb, v212
	v_med3_i32 v208, v207, 0, v249
	v_med3_i32 v207, v207, s75, v250
	v_med3_i32 v175, v168, 0, v249
	v_med3_i32 v168, v168, s75, v250
	v_lshl_add_u32 v213, v207, 2, s69
	v_add_u32_e32 v207, 0xd2, v212
	v_lshl_add_u32 v169, v169, 2, s69
	v_lshl_add_u32 v171, v171, 2, s69
	v_lshl_add_u32 v173, v173, 2, s69
	v_lshl_add_u32 v175, v175, 2, s69
	v_lshl_add_u32 v201, v168, 2, s69
	v_lshl_add_u32 v209, v208, 2, s69
	v_med3_i32 v208, v207, 0, v249
	v_med3_i32 v207, v207, s75, v250
	ds_read_b32 v168, v169
	ds_read_b32 v170, v170 offset:128
	ds_read_b32 v169, v171
	ds_read_b32 v171, v172 offset:128
	ds_read_b32 v172, v173
	ds_read_b32 v174, v174 offset:128
	ds_read_b32 v173, v175
	ds_read_b32 v175, v201 offset:128
	v_add_u32_e32 v201, 0xd0, v212
	v_lshl_add_u32 v217, v207, 2, s69
	v_add_u32_e32 v207, 0xd3, v212
	v_med3_i32 v206, v201, 0, v249
	v_lshl_add_u32 v214, v208, 2, s69
	v_med3_i32 v208, v207, 0, v249
	v_med3_i32 v201, v201, s75, v250
	v_lshl_add_u32 v206, v206, 2, s69
	v_med3_i32 v207, v207, s75, v250
	v_lshl_add_u32 v219, v208, 2, s69
	v_lshl_add_u32 v201, v201, 2, s69
	v_lshl_add_u32 v220, v207, 2, s69
	ds_read_b32 v206, v206
	ds_read_b32 v208, v201 offset:128
	ds_read_b32 v207, v209
	ds_read_b32 v209, v213 offset:128
	ds_read_b32 v216, v214
	ds_read_b32 v218, v217 offset:128
	ds_read_b32 v217, v219
	ds_read_b32 v219, v220 offset:128
	v_add_u32_e32 v214, 0xd9, v212
	v_med3_i32 v220, v214, 0, v249
	v_lshl_add_u32 v221, v220, 2, s69
	v_add_u32_e32 v220, 0xda, v212
	v_med3_i32 v222, v220, 0, v249
	v_med3_i32 v220, v220, s75, v250
	v_add_u32_e32 v201, 0xd8, v212
	v_lshl_add_u32 v226, v220, 2, s69
	v_add_u32_e32 v220, 0xdb, v212
	v_med3_i32 v213, v201, 0, v249
	v_lshl_add_u32 v223, v222, 2, s69
	v_med3_i32 v222, v220, 0, v249
	v_med3_i32 v220, v220, s75, v250
	v_med3_i32 v201, v201, s75, v250
	v_lshl_add_u32 v213, v213, 2, s69
	v_med3_i32 v214, v214, s75, v250
	v_lshl_add_u32 v225, v222, 2, s69
	v_lshl_add_u32 v227, v220, 2, s69
	v_lshl_add_u32 v201, v201, 2, s69
	v_lshl_add_u32 v214, v214, 2, s69
	ds_read_b32 v220, v213
	ds_read_b32 v222, v201 offset:128
	ds_read_b32 v224, v223
	ds_read_b32 v225, v225
	ds_read_b32 v221, v221
	ds_read_b32 v227, v227 offset:128
	ds_read_b32 v226, v226 offset:128
	ds_read_b32 v223, v214 offset:128
	s_waitcnt lgkmcnt(4)
; #define SBAR() __builtin_amdgcn_sched_barrier(0)
; __device__ __forceinline__ float max3f(float a, float b, float c) { float r; asm("v_max3_f32 %0, %1, %2, %3" : "=v"(r) : "v"(a), "v"(b), "v"(c)); return r; }
; #define VRD8(D0, L0, H0, L1, H1, L2, H2, L3, H3) do { L0 = tr_read<v_rd_off(D0, 0, 0)>(vb); H0 = tr_read<v_rd_off(D0, 0, 1)>(vb); L1 = tr_read<v_rd_off(D0, 1, 0)>(vb); H1 = tr_read<v_rd_off(D0, 1, 1)>(vb); \
;     L2 = tr_read<v_rd_off(D0, 2, 0)>(vb); H2 = tr_read<v_rd_off(D0, 2, 1)>(vb); L3 = tr_read<v_rd_off(D0, 3, 0)>(vb); H3 = tr_read<v_rd_off(D0, 3, 1)>(vb); } while (0)
; __device__ __forceinline__ void pv_partial(f32x16* o, int vb, bf16x8 pa0, bf16x8 pa1, bf16x8 pa2, bf16x8 pa3, f32x16& p0, f32x16& p1, float& m_ref, f32x16& negm, float& alpha) {
;   s16x4 a0, a1, a2, a3, a4, a5, a6, a7, b0, b1, b2, b3, b4, b5, b6, b7;
;   VRD8(0, a0, a1, a2, a3, a4, a5, a6, a7);
;   VRD8(1, b0, b1, b2, b3, b4, b5, b6, b7);
;   asm volatile("s_waitcnt lgkmcnt(8)" ::: "memory"); SBAR();
;   MMA4(o[0], a0, a1, a2, a3, a4, a5, a6, a7);
;   float pmax = max3f(p0[0], p0[1], p1[0]), pmb = max3f(p0[2], p0[3], p1[1]);
;   pmax = max3f(pmax, p1[2], p1[3]);
; #pragma unroll
;   for (int r = 4; r < 16; r += 4) { pmax = max3f(pmax, p0[r], p0[r + 1]); pmb = max3f(pmb, p0[r + 2], p0[r + 3]); pmax = max3f(pmax, p1[r], p1[r + 1]); pmb = max3f(pmb, p1[r + 2], p1[r + 3]); }
;   pmax = max3f(pmax, pmb, pmb);
;   SBAR();
;   VRD8(2, a0, a1, a2, a3, a4, a5, a6, a7);
;   asm volatile("s_waitcnt lgkmcnt(8)" ::: "memory"); SBAR();
;   MMA4(o[1], b0, b1, b2, b3, b4, b5, b6, b7);
;   { auto rr = __builtin_amdgcn_permlane32_swap(__float_as_uint(pmax), __float_as_uint(pmax), false, false);
;     pmax = fmaxf(__uint_as_float(rr[0]), __uint_as_float(rr[1])); }
;   alpha = 1.f;
;   if (!__builtin_expect(__all(pmax <= THR), 1)) {
;     const float dl = fmaxf(pmax, 0.f); m_ref += dl; alpha = __builtin_amdgcn_exp2f(-dl);
; #pragma unroll
;     for (int r = 0; r < 16; ++r) { p0[r] -= dl; p1[r] -= dl; negm[r] -= dl; }
;   }
	v_pk_add_f32 v[126:127], v[126:127], v[224:225]
	s_waitcnt lgkmcnt(3)
	v_pk_add_f32 v[124:125], v[124:125], v[220:221]
	v_pk_add_f32 v[122:123], v[122:123], v[216:217]
	v_pk_add_f32 v[120:121], v[120:121], v[206:207]
	v_pk_add_f32 v[118:119], v[118:119], v[172:173]
	v_pk_add_f32 v[116:117], v[116:117], v[168:169]
	v_pk_add_f32 v[114:115], v[114:115], v[164:165]
	v_pk_add_f32 v[112:113], v[112:113], v[160:161]
	s_waitcnt lgkmcnt(1)
	v_pk_add_f32 v[110:111], v[110:111], v[226:227]
	s_waitcnt lgkmcnt(0)
	v_pk_add_f32 v[108:109], v[108:109], v[222:223]
	v_pk_add_f32 v[106:107], v[106:107], v[218:219]
	v_pk_add_f32 v[104:105], v[104:105], v[208:209]
	v_pk_add_f32 v[102:103], v[102:103], v[174:175]
	v_pk_add_f32 v[100:101], v[100:101], v[170:171]
	v_pk_add_f32 v[98:99], v[98:99], v[166:167]
	v_pk_add_f32 v[96:97], v[96:97], v[162:163]
.LBB0_168:
	v_add_u32_e32 v201, s43, v199
	ds_read_b64_tr_b16 v[160:161], v201 offset:0
	ds_read_b64_tr_b16 v[162:163], v201 offset:0x800
	ds_read_b64_tr_b16 v[164:165], v201 offset:0x1000
	ds_read_b64_tr_b16 v[166:167], v201 offset:0x1800
	ds_read_b64_tr_b16 v[168:169], v201 offset:0x2000
	ds_read_b64_tr_b16 v[170:171], v201 offset:0x2800
	ds_read_b64_tr_b16 v[172:173], v201 offset:0x3000
	ds_read_b64_tr_b16 v[174:175], v201 offset:0x3800
	ds_read_b64_tr_b16 v[216:217], v201 offset:0x200
	ds_read_b64_tr_b16 v[218:219], v201 offset:0xa00
	ds_read_b64_tr_b16 v[220:221], v201 offset:0x1200
	ds_read_b64_tr_b16 v[222:223], v201 offset:0x1a00
	ds_read_b64_tr_b16 v[224:225], v201 offset:0x2200
	ds_read_b64_tr_b16 v[226:227], v201 offset:0x2a00
	ds_read_b64_tr_b16 v[228:229], v201 offset:0x3200
	ds_read_b64_tr_b16 v[230:231], v201 offset:0x3a00
	s_waitcnt lgkmcnt(8)
	s_nop 0
	v_mfma_f32_32x32x16_bf16 v[0:15], v[80:83], v[160:163], v[0:15]
	v_max3_f32 v160, v112, v113, v96
	v_max3_f32 v161, v114, v115, v97
	v_max3_f32 v160, v160, v98, v99
	v_max3_f32 v161, v161, v118, v119
	v_max3_f32 v160, v160, v116, v117
	v_mfma_f32_32x32x16_bf16 v[0:15], v[88:91], v[164:167], v[0:15]
	v_max3_f32 v160, v160, v100, v101
	v_max3_f32 v161, v161, v102, v103
	v_max3_f32 v160, v160, v120, v121
	v_max3_f32 v161, v161, v122, v123
	v_max3_f32 v160, v160, v104, v105
	v_mfma_f32_32x32x16_bf16 v[0:15], v[84:87], v[168:171], v[0:15]
	v_max3_f32 v161, v161, v106, v107
	v_max3_f32 v160, v160, v124, v125
	v_max3_f32 v161, v161, v126, v127
	v_max3_f32 v160, v160, v108, v109
	v_max3_f32 v161, v161, v110, v111
	v_mfma_f32_32x32x16_bf16 v[0:15], v[92:95], v[172:175], v[0:15]
	v_max3_f32 v206, v160, v161, v161
	ds_read_b64_tr_b16 v[172:173], v201 offset:0x400
	ds_read_b64_tr_b16 v[174:175], v201 offset:0xc00
	ds_read_b64_tr_b16 v[168:169], v201 offset:0x1400
	ds_read_b64_tr_b16 v[170:171], v201 offset:0x1c00
	ds_read_b64_tr_b16 v[164:165], v201 offset:0x2400
	ds_read_b64_tr_b16 v[166:167], v201 offset:0x2c00
	ds_read_b64_tr_b16 v[160:161], v201 offset:0x3400
	ds_read_b64_tr_b16 v[162:163], v201 offset:0x3c00
	s_waitcnt lgkmcnt(8)
	v_mfma_f32_32x32x16_bf16 v[48:63], v[80:83], v[216:219], v[48:63]
	v_mov_b32_e32 v207, v206
	s_nop 1
	v_permlane32_swap_b32_e32 v206, v207
	v_max_f32_e32 v213, v206, v207
	v_cmp_ge_f32_e32 vcc, s76, v213
	v_mfma_f32_32x32x16_bf16 v[48:63], v[88:91], v[220:223], v[48:63]
	s_cmp_eq_u64 vcc, exec
	v_mfma_f32_32x32x16_bf16 v[48:63], v[84:87], v[224:227], v[48:63]
	v_mfma_f32_32x32x16_bf16 v[48:63], v[92:95], v[228:231], v[48:63]
	s_cbranch_scc0 .LBB0_187
	v_mov_b32_e32 v213, 1.0
	s_mov_b64 vcc, 0
; #define SBAR() __builtin_amdgcn_sched_barrier(0)
; #define VRD8(D0, L0, H0, L1, H1, L2, H2, L3, H3) do { L0 = tr_read<v_rd_off(D0, 0, 0)>(vb); H0 = tr_read<v_rd_off(D0, 0, 1)>(vb); L1 = tr_read<v_rd_off(D0, 1, 0)>(vb); H1 = tr_read<v_rd_off(D0, 1, 1)>(vb); \
;     L2 = tr_read<v_rd_off(D0, 2, 0)>(vb); H2 = tr_read<v_rd_off(D0, 2, 1)>(vb); L3 = tr_read<v_rd_off(D0, 3, 0)>(vb); H3 = tr_read<v_rd_off(D0, 3, 1)>(vb); } while (0)
; #define MMA4(OD, L0, H0, L1, H1, L2, H2, L3, H3) do { OD = __builtin_amdgcn_mfma_f32_32x32x16_bf16(pa0, PK(L0, H0), OD, 0, 0, 0); OD = __builtin_amdgcn_mfma_f32_32x32x16_bf16(pa1, PK(L1, H1), OD, 0, 0, 0); \
;     OD = __builtin_amdgcn_mfma_f32_32x32x16_bf16(pa2, PK(L2, H2), OD, 0, 0, 0); OD = __builtin_amdgcn_mfma_f32_32x32x16_bf16(pa3, PK(L3, H3), OD, 0, 0, 0); } while (0)
; __device__ __forceinline__ void pv_partial(f32x16* o, int vb, bf16x8 pa0, bf16x8 pa1, bf16x8 pa2, bf16x8 pa3, f32x16& p0, f32x16& p1, float& m_ref, f32x16& negm, float& alpha) {
;     ...
;   VRD8(3, b0, b1, b2, b3, b4, b5, b6, b7);
;   asm volatile("s_waitcnt lgkmcnt(8)" ::: "memory"); SBAR();
;   MMA4(o[2], a0, a1, a2, a3, a4, a5, a6, a7);
; #pragma unroll
;   for (int r = 0; r < 8; ++r) p0[r] = __builtin_amdgcn_exp2f(p0[r]);
;   SBAR();
;   asm volatile("s_waitcnt lgkmcnt(0)" ::: "memory"); SBAR();
;   MMA4(o[3], b0, b1, b2, b3, b4, b5, b6, b7);
; #pragma unroll
;   for (int r = 8; r < 16; ++r) p0[r] = __builtin_amdgcn_exp2f(p0[r]);
; }
.LBB0_170:
	ds_read_b64_tr_b16 v[216:217], v201 offset:0x600
	ds_read_b64_tr_b16 v[218:219], v201 offset:0xe00
	ds_read_b64_tr_b16 v[220:221], v201 offset:0x1600
	ds_read_b64_tr_b16 v[222:223], v201 offset:0x1e00
	ds_read_b64_tr_b16 v[224:225], v201 offset:0x2600
	ds_read_b64_tr_b16 v[226:227], v201 offset:0x2e00
	ds_read_b64_tr_b16 v[228:229], v201 offset:0x3600
	ds_read_b64_tr_b16 v[230:231], v201 offset:0x3e00
	s_waitcnt lgkmcnt(8)
	v_mfma_f32_32x32x16_bf16 v[32:47], v[80:83], v[172:175], v[32:47]
	v_mfma_f32_32x32x16_bf16 v[32:47], v[88:91], v[168:171], v[32:47]
	v_mfma_f32_32x32x16_bf16 v[32:47], v[84:87], v[164:167], v[32:47]
	v_mfma_f32_32x32x16_bf16 v[32:47], v[92:95], v[160:163], v[32:47]
	s_waitcnt lgkmcnt(0)
	v_mfma_f32_32x32x16_bf16 v[16:31], v[80:83], v[216:219], v[16:31]
	s_add_i32 s79, s18, 0
	v_mfma_f32_32x32x16_bf16 v[16:31], v[88:91], v[220:223], v[16:31]
	v_mfma_f32_32x32x16_bf16 v[16:31], v[84:87], v[224:227], v[16:31]
	v_mfma_f32_32x32x16_bf16 v[16:31], v[92:95], v[228:231], v[16:31]
	s_cbranch_vccz .LBB0_174
	s_and_saveexec_b64 s[10:11], s[0:1]
	ds_write_b32 v186, v213 offset:128
	s_or_b64 exec, exec, s[10:11]
	s_waitcnt lgkmcnt(0)
	v_add_u32_e32 v92, s49, v204
	ds_read_b128 v[80:83], v92 offset:224
	ds_read_b128 v[84:87], v92 offset:192
	ds_read_b128 v[88:91], v92 offset:160
	ds_read_b128 v[92:95], v92 offset:128
	s_waitcnt lgkmcnt(3)
	v_pk_mul_f32 v[12:13], v[12:13], v[80:81]
	s_waitcnt lgkmcnt(2)
	v_pk_mul_f32 v[8:9], v[8:9], v[84:85]
	s_waitcnt lgkmcnt(1)
	v_pk_mul_f32 v[4:5], v[4:5], v[88:89]
	v_pk_mul_f32 v[14:15], v[14:15], v[82:83]
	v_pk_mul_f32 v[10:11], v[10:11], v[86:87]
	v_pk_mul_f32 v[6:7], v[6:7], v[90:91]
	s_waitcnt lgkmcnt(0)
	v_pk_mul_f32 v[2:3], v[2:3], v[94:95]
	v_pk_mul_f32 v[0:1], v[0:1], v[92:93]
	v_pk_mul_f32 v[60:61], v[60:61], v[80:81]
	v_pk_mul_f32 v[56:57], v[56:57], v[84:85]
	v_pk_mul_f32 v[52:53], v[52:53], v[88:89]
	v_pk_mul_f32 v[62:63], v[62:63], v[82:83]
	v_pk_mul_f32 v[58:59], v[58:59], v[86:87]
	v_pk_mul_f32 v[54:55], v[54:55], v[90:91]
	v_pk_mul_f32 v[50:51], v[50:51], v[94:95]
	v_pk_mul_f32 v[48:49], v[48:49], v[92:93]
	v_pk_mul_f32 v[44:45], v[44:45], v[80:81]
	v_pk_mul_f32 v[40:41], v[40:41], v[84:85]
	v_pk_mul_f32 v[36:37], v[36:37], v[88:89]
	v_pk_mul_f32 v[46:47], v[46:47], v[82:83]
	v_pk_mul_f32 v[42:43], v[42:43], v[86:87]
	v_pk_mul_f32 v[38:39], v[38:39], v[90:91]
	v_pk_mul_f32 v[34:35], v[34:35], v[94:95]
	v_pk_mul_f32 v[32:33], v[32:33], v[92:93]
	v_pk_mul_f32 v[28:29], v[28:29], v[80:81]
	v_pk_mul_f32 v[24:25], v[24:25], v[84:85]
	v_pk_mul_f32 v[20:21], v[20:21], v[88:89]
	v_pk_mul_f32 v[30:31], v[30:31], v[82:83]
	v_pk_mul_f32 v[26:27], v[26:27], v[86:87]
	v_pk_mul_f32 v[22:23], v[22:23], v[90:91]
	v_pk_mul_f32 v[18:19], v[18:19], v[94:95]
	v_pk_mul_f32 v[16:17], v[16:17], v[92:93]
.LBB0_174:
	s_addk_i32 s56, 0x80
	s_waitcnt vmcnt(0)
	s_waitcnt lgkmcnt(0)
	s_barrier
	s_lshl_b32 m0, s62, 11
	s_add_i32 m0, m0, s43
	s_nop 0
	global_load_lds_dwordx4 v236, s[100:101]
	global_load_lds_dwordx4 v237, s[100:101] offset:1024
	s_addk_i32 m0, 0x4000
	s_nop 0
	global_load_lds_dwordx4 v234, s[100:101]
	global_load_lds_dwordx4 v235, s[100:101] offset:1024
	s_add_u32 s100, s100, 0x90000
	s_addc_u32 s101, s101, 0
	s_addk_i32 s78, 0xbf
	s_cmpk_gt_i32 s78, 0xff80
	s_cselect_b64 s[10:11], -1, 0
	s_cmp_lt_u32 s56, s19
	s_cselect_b64 s[80:81], -1, 0
	s_and_b64 s[10:11], s[10:11], s[80:81]
	s_cmpk_lt_i32 s78, 0xff81
	s_cselect_b64 vcc, -1, 0
	v_cndmask_b32_e32 v80, v200, v195, vcc
	v_cndmask_b32_e64 v214, v80, 0, s[10:11]
	v_cmp_eq_f32_e32 vcc, v214, v215
	s_cbranch_vccnz .LBB0_176
	v_sub_f32_e32 v80, v214, v215
	v_pk_add_f32 v[78:79], v[80:81], v[78:79] op_sel_hi:[0,1]
	v_pk_add_f32 v[76:77], v[80:81], v[76:77] op_sel_hi:[0,1]
	v_pk_add_f32 v[74:75], v[80:81], v[74:75] op_sel_hi:[0,1]
	v_pk_add_f32 v[72:73], v[80:81], v[72:73] op_sel_hi:[0,1]
	v_pk_add_f32 v[70:71], v[80:81], v[70:71] op_sel_hi:[0,1]
	v_pk_add_f32 v[68:69], v[80:81], v[68:69] op_sel_hi:[0,1]
	v_pk_add_f32 v[66:67], v[80:81], v[66:67] op_sel_hi:[0,1]
	v_pk_add_f32 v[64:65], v[80:81], v[64:65] op_sel_hi:[0,1]
	s_branch .LBB0_177

; __device__ __forceinline__ unsigned cvtpk(float lo, float hi) { unsigned r; asm volatile("v_cvt_pk_bf16_f32 %0, %1, %2" : "=v"(r) : "v"(lo), "v"(hi)); return r; }
; __device__ __forceinline__ void finishSM(f32x16& p0, f32x16& p1, float alpha, float& l_reg, bf16x8& pa0, bf16x8& pa1, bf16x8& pa2, bf16x8& pa3) {
; #pragma unroll
;   for (int r = 0; r < 16; ++r) p1[r] = __builtin_amdgcn_exp2f(p1[r]);
;   float ps = 0;
; #pragma unroll
;   for (int r = 0; r < 16; ++r) ps += p0[r];
; #pragma unroll
;   for (int r = 0; r < 16; ++r) ps += p1[r];
;   { auto rr = __builtin_amdgcn_permlane32_swap(__float_as_uint(ps), __float_as_uint(ps), false, false);
;     ps = __uint_as_float(rr[0]) + __uint_as_float(rr[1]); }
;   l_reg = l_reg * alpha + ps;
;     ...
;   PK4(p0, 0, pa0); PK4(p0, 8, pa1); PK4(p1, 0, pa2); PK4(p1, 8, pa3);
;     ...
; }
; __device__ __forceinline__ bf16x8 scale_bf16x8(bf16x8 v, float c) {
;   u32x4 w = *reinterpret_cast<u32x4*>(&v), o;
; #pragma unroll
;   for (int i = 0; i < 4; ++i) { const float lo = __uint_as_float(w[i] << 16), hh = __uint_as_float(w[i] & 0xffff0000u); o[i] = cvtpk(lo * c, hh * c); }
;   return *reinterpret_cast<bf16x8*>(&o);
; }
; template <int ND0> __device__ __forceinline__ void qkt(f32x16& p0, f32x16& p1, const char* Ks, const bf16x8* qr, int r32, int hi, int cboff, const f32x16& ci) {
; #pragma unroll
;   for (int d0 = 0; d0 < ND0; ++d0) { int cb = cboff + (d0 * 16 + hi * 8) * 2;
;     bf16x8 b0 = *reinterpret_cast<const bf16x8*>(Ks + KSWZ(r32, cb));
;     bf16x8 b1 = *reinterpret_cast<const bf16x8*>(Ks + KSWZ(32 + r32, cb));
;     if (d0 == 0) { p0 = __builtin_amdgcn_mfma_f32_32x32x16_bf16(b0, qr[0], ci, 0, 0, 0); p1 = __builtin_amdgcn_mfma_f32_32x32x16_bf16(b1, qr[0], ci, 0, 0, 0); }
;     else { p0 = __builtin_amdgcn_mfma_f32_32x32x16_bf16(b0, qr[d0], p0, 0, 0, 0); p1 = __builtin_amdgcn_mfma_f32_32x32x16_bf16(b1, qr[d0], p1, 0, 0, 0); } }
; }
.LBB0_177:
	v_exp_f32_e32 v168, v112
	v_exp_f32_e32 v169, v113
	v_exp_f32_e32 v170, v114
	v_exp_f32_e32 v171, v115
	v_exp_f32_e32 v172, v116
	v_exp_f32_e32 v173, v117
	v_exp_f32_e32 v174, v118
	v_exp_f32_e32 v175, v119
	v_exp_f32_e32 v206, v120
	v_exp_f32_e32 v207, v121
	v_exp_f32_e32 v208, v122
	v_exp_f32_e32 v209, v123
	v_exp_f32_e32 v217, v124
	v_exp_f32_e32 v218, v125
	v_exp_f32_e32 v219, v126
	v_exp_f32_e32 v220, v127
	v_add_u32_e32 v80, s79, v188
	ds_read_b128 v[160:163], v80 offset:24576
	ds_read_b128 v[80:83], v80 offset:16384
	v_add_u32_e32 v164, s79, v196
	v_exp_f32_e32 v96, v96
	v_exp_f32_e32 v97, v97
	v_exp_f32_e32 v98, v98
	s_waitcnt lgkmcnt(0)
	v_mfma_f32_32x32x16_bf16 v[112:127], v[80:83], v[128:131], v[64:79]
	v_exp_f32_e32 v99, v99
	v_exp_f32_e32 v100, v100
	v_exp_f32_e32 v101, v101
	v_exp_f32_e32 v102, v102
	v_exp_f32_e32 v103, v103
	v_mfma_f32_32x32x16_bf16 v[80:95], v[160:163], v[128:131], v[64:79]
	ds_read_b128 v[160:163], v164 offset:24576
	ds_read_b128 v[164:167], v164 offset:16384
	s_waitcnt lgkmcnt(1)
	v_mfma_f32_32x32x16_bf16 v[80:95], v[160:163], v[132:135], v[80:95]
	s_waitcnt lgkmcnt(0)
	v_mfma_f32_32x32x16_bf16 v[112:127], v[164:167], v[132:135], v[112:127]
	v_add_u32_e32 v164, s79, v190
	ds_read_b128 v[160:163], v164 offset:24576
	ds_read_b128 v[164:167], v164 offset:16384
	s_waitcnt lgkmcnt(1)
	v_mfma_f32_32x32x16_bf16 v[80:95], v[160:163], v[136:139], v[80:95]
	s_waitcnt lgkmcnt(0)
	v_mfma_f32_32x32x16_bf16 v[112:127], v[164:167], v[136:139], v[112:127]
	v_add_u32_e32 v164, s79, v189
	ds_read_b128 v[160:163], v164 offset:24576
	ds_read_b128 v[164:167], v164 offset:16384
	s_waitcnt lgkmcnt(1)
	v_mfma_f32_32x32x16_bf16 v[80:95], v[160:163], v[140:143], v[80:95]
	v_exp_f32_e32 v160, v104
	v_pk_add_f32 v[144:145], v[168:169], v[170:171]
	v_pk_add_f32 v[144:145], v[144:145], v[172:173]
	v_pk_add_f32 v[144:145], v[144:145], v[174:175]
	v_pk_add_f32 v[144:145], v[144:145], v[206:207]
	v_pk_add_f32 v[144:145], v[144:145], v[208:209]
	v_pk_add_f32 v[144:145], v[144:145], v[218:219]
	v_pk_add_f32 v[144:145], v[144:145], v[96:97]
	v_pk_add_f32 v[144:145], v[144:145], v[98:99]
	v_pk_add_f32 v[144:145], v[144:145], v[100:101]
	v_exp_f32_e32 v161, v105
	v_pk_add_f32 v[144:145], v[144:145], v[102:103]
	v_exp_f32_e32 v162, v106
	v_add_f32_e32 v104, v217, v220
	v_exp_f32_e32 v163, v107
	s_waitcnt lgkmcnt(0)
	v_mfma_f32_32x32x16_bf16 v[112:127], v[164:167], v[140:143], v[112:127]
	v_exp_f32_e32 v164, v108
	v_exp_f32_e32 v165, v109
	v_exp_f32_e32 v166, v110
	v_exp_f32_e32 v167, v111
	v_pk_add_f32 v[144:145], v[144:145], v[160:161]
	v_pk_add_f32 v[144:145], v[144:145], v[162:163]
	v_pk_add_f32 v[144:145], v[144:145], v[164:165]
	v_pk_add_f32 v[144:145], v[144:145], v[166:167]
	v_add_f32_e32 v104, v144, v104
	v_add_f32_e32 v215, v145, v104
	v_cvt_pk_bf16_f32 v104, v168, v169
	v_cvt_pk_bf16_f32 v105, v170, v171
	v_cvt_pk_bf16_f32 v106, v172, v173
	v_cvt_pk_bf16_f32 v107, v174, v175
	v_cvt_pk_bf16_f32 v108, v206, v207
	v_cvt_pk_bf16_f32 v109, v208, v209
	v_cvt_pk_bf16_f32 v110, v217, v218
	v_cvt_pk_bf16_f32 v111, v219, v220
	v_cvt_pk_bf16_f32 v96, v96, v97
	v_cvt_pk_bf16_f32 v97, v98, v99
	v_cvt_pk_bf16_f32 v98, v100, v101
	v_cvt_pk_bf16_f32 v99, v102, v103
	v_cvt_pk_bf16_f32 v100, v160, v161
	v_cvt_pk_bf16_f32 v101, v162, v163
	v_cvt_pk_bf16_f32 v102, v164, v165
	v_cvt_pk_bf16_f32 v103, v166, v167
	s_andn2_b64 vcc, exec, s[10:11]
	s_cbranch_vccnz .LBB0_179
	v_add_u32_e32 v160, 0x100, v212
	v_med3_i32 v161, v160, 0, v249
	v_med3_i32 v160, v160, s75, v250
	v_lshl_add_u32 v162, v160, 2, s69
	v_add_u32_e32 v160, 0x101, v212
	v_med3_i32 v163, v160, 0, v249
	v_med3_i32 v160, v160, s75, v250
	v_lshl_add_u32 v164, v160, 2, s69
	v_add_u32_e32 v160, 0x102, v212
	v_med3_i32 v165, v160, 0, v249
	v_med3_i32 v160, v160, s75, v250
	v_lshl_add_u32 v166, v160, 2, s69
	v_add_u32_e32 v160, 0x103, v212
	v_med3_i32 v167, v160, 0, v249
	v_med3_i32 v160, v160, s75, v250
	v_lshl_add_u32 v161, v161, 2, s69
	v_lshl_add_u32 v163, v163, 2, s69
	v_lshl_add_u32 v165, v165, 2, s69
	v_lshl_add_u32 v167, v167, 2, s69
	v_lshl_add_u32 v168, v160, 2, s69
	ds_read_b32 v160, v161
	ds_read_b32 v162, v162 offset:128
	ds_read_b32 v161, v163
	ds_read_b32 v163, v164 offset:128
	ds_read_b32 v164, v165
	ds_read_b32 v166, v166 offset:128
	ds_read_b32 v165, v167
	ds_read_b32 v167, v168 offset:128
	v_add_u32_e32 v168, 0x108, v212
	v_med3_i32 v169, v168, 0, v249
	v_med3_i32 v168, v168, s75, v250
	v_lshl_add_u32 v170, v168, 2, s69
	v_add_u32_e32 v168, 0x109, v212
	v_med3_i32 v171, v168, 0, v249
	v_med3_i32 v168, v168, s75, v250
	v_lshl_add_u32 v172, v168, 2, s69
	v_add_u32_e32 v168, 0x10a, v212
	v_med3_i32 v173, v168, 0, v249
	v_med3_i32 v168, v168, s75, v250
	v_lshl_add_u32 v174, v168, 2, s69
	v_add_u32_e32 v168, 0x10b, v212
	v_med3_i32 v175, v168, 0, v249
	v_med3_i32 v168, v168, s75, v250
	v_lshl_add_u32 v169, v169, 2, s69
	v_lshl_add_u32 v171, v171, 2, s69
	v_lshl_add_u32 v173, v173, 2, s69
	v_lshl_add_u32 v175, v175, 2, s69
	v_lshl_add_u32 v206, v168, 2, s69
	ds_read_b32 v168, v169
	ds_read_b32 v170, v170 offset:128
	ds_read_b32 v169, v171
	ds_read_b32 v171, v172 offset:128
	ds_read_b32 v172, v173
	ds_read_b32 v174, v174 offset:128
	ds_read_b32 v173, v175
	ds_read_b32 v175, v206 offset:128
	v_add_u32_e32 v206, 0x110, v212
	v_med3_i32 v207, v206, 0, v249
	v_med3_i32 v206, v206, s75, v250
	v_lshl_add_u32 v208, v206, 2, s69
	v_add_u32_e32 v206, 0x111, v212
	v_med3_i32 v209, v206, 0, v249
	v_med3_i32 v206, v206, s75, v250
	v_lshl_add_u32 v217, v206, 2, s69
	v_add_u32_e32 v206, 0x112, v212
	v_med3_i32 v218, v206, 0, v249
	v_med3_i32 v206, v206, s75, v250
	v_lshl_add_u32 v219, v206, 2, s69
; #define SBAR() __builtin_amdgcn_sched_barrier(0)
; __device__ __forceinline__ float max3f(float a, float b, float c) { float r; asm("v_max3_f32 %0, %1, %2, %3" : "=v"(r) : "v"(a), "v"(b), "v"(c)); return r; }
; #define VRD8(D0, L0, H0, L1, H1, L2, H2, L3, H3) do { L0 = tr_read<v_rd_off(D0, 0, 0)>(vb); H0 = tr_read<v_rd_off(D0, 0, 1)>(vb); L1 = tr_read<v_rd_off(D0, 1, 0)>(vb); H1 = tr_read<v_rd_off(D0, 1, 1)>(vb); \
;     L2 = tr_read<v_rd_off(D0, 2, 0)>(vb); H2 = tr_read<v_rd_off(D0, 2, 1)>(vb); L3 = tr_read<v_rd_off(D0, 3, 0)>(vb); H3 = tr_read<v_rd_off(D0, 3, 1)>(vb); } while (0)
; #define MMA4(OD, L0, H0, L1, H1, L2, H2, L3, H3) do { OD = __builtin_amdgcn_mfma_f32_32x32x16_bf16(pa0, PK(L0, H0), OD, 0, 0, 0); OD = __builtin_amdgcn_mfma_f32_32x32x16_bf16(pa1, PK(L1, H1), OD, 0, 0, 0); \
;     OD = __builtin_amdgcn_mfma_f32_32x32x16_bf16(pa2, PK(L2, H2), OD, 0, 0, 0); OD = __builtin_amdgcn_mfma_f32_32x32x16_bf16(pa3, PK(L3, H3), OD, 0, 0, 0); } while (0)
; __device__ __forceinline__ void pv_partial(f32x16* o, int vb, bf16x8 pa0, bf16x8 pa1, bf16x8 pa2, bf16x8 pa3, f32x16& p0, f32x16& p1, float& m_ref, f32x16& negm, float& alpha) {
;   s16x4 a0, a1, a2, a3, a4, a5, a6, a7, b0, b1, b2, b3, b4, b5, b6, b7;
;   VRD8(0, a0, a1, a2, a3, a4, a5, a6, a7);
;   VRD8(1, b0, b1, b2, b3, b4, b5, b6, b7);
;   asm volatile("s_waitcnt lgkmcnt(8)" ::: "memory"); SBAR();
;   MMA4(o[0], a0, a1, a2, a3, a4, a5, a6, a7);
;   float pmax = max3f(p0[0], p0[1], p1[0]), pmb = max3f(p0[2], p0[3], p1[1]);
;   pmax = max3f(pmax, p1[2], p1[3]);
; #pragma unroll
;   for (int r = 4; r < 16; r += 4) { pmax = max3f(pmax, p0[r], p0[r + 1]); pmb = max3f(pmb, p0[r + 2], p0[r + 3]); pmax = max3f(pmax, p1[r], p1[r + 1]); pmb = max3f(pmb, p1[r + 2], p1[r + 3]); }
;   pmax = max3f(pmax, pmb, pmb);
;   SBAR();
;   VRD8(2, a0, a1, a2, a3, a4, a5, a6, a7);
;   asm volatile("s_waitcnt lgkmcnt(8)" ::: "memory"); SBAR();
;   MMA4(o[1], b0, b1, b2, b3, b4, b5, b6, b7);
;   { auto rr = __builtin_amdgcn_permlane32_swap(__float_as_uint(pmax), __float_as_uint(pmax), false, false);
;     pmax = fmaxf(__uint_as_float(rr[0]), __uint_as_float(rr[1])); }
;   alpha = 1.f;
;   if (!__builtin_expect(__all(pmax <= THR), 1)) {
;     const float dl = fmaxf(pmax, 0.f); m_ref += dl; alpha = __builtin_amdgcn_exp2f(-dl);
	v_add_u32_e32 v206, 0x113, v212
	v_add_u32_e32 v223, 0x119, v212
	v_med3_i32 v220, v206, 0, v249
	v_med3_i32 v224, v223, 0, v249
	v_med3_i32 v223, v223, s75, v250
	v_lshl_add_u32 v207, v207, 2, s69
	v_lshl_add_u32 v209, v209, 2, s69
	v_lshl_add_u32 v218, v218, 2, s69
	v_med3_i32 v206, v206, s75, v250
	v_lshl_add_u32 v221, v220, 2, s69
	v_lshl_add_u32 v230, v223, 2, s69
	v_add_u32_e32 v223, 0x11a, v212
	v_lshl_add_u32 v222, v206, 2, s69
	ds_read_b32 v206, v207
	ds_read_b32 v208, v208 offset:128
	ds_read_b32 v207, v209
	ds_read_b32 v209, v217 offset:128
	ds_read_b32 v218, v218
	ds_read_b32 v220, v219 offset:128
	ds_read_b32 v219, v221
	ds_read_b32 v221, v222 offset:128
	v_add_u32_e32 v217, 0x118, v212
	v_lshl_add_u32 v225, v224, 2, s69
	v_med3_i32 v224, v223, 0, v249
	v_med3_i32 v223, v223, s75, v250
	v_add_u32_e32 v212, 0x11b, v212
	v_med3_i32 v222, v217, 0, v249
	v_lshl_add_u32 v228, v223, 2, s69
	v_med3_i32 v223, v212, 0, v249
	v_med3_i32 v217, v217, s75, v250
	v_lshl_add_u32 v222, v222, 2, s69
	v_lshl_add_u32 v226, v224, 2, s69
	v_med3_i32 v212, v212, s75, v250
	v_lshl_add_u32 v223, v223, 2, s69
	v_lshl_add_u32 v217, v217, 2, s69
	v_lshl_add_u32 v212, v212, 2, s69
	ds_read_b32 v222, v222
	ds_read_b32 v224, v217 offset:128
	ds_read_b32 v226, v226
	ds_read_b32 v227, v223
	ds_read_b32 v223, v225
	ds_read_b32 v229, v212 offset:128
	ds_read_b32 v228, v228 offset:128
	ds_read_b32 v225, v230 offset:128
	s_waitcnt lgkmcnt(4)
	v_pk_add_f32 v[126:127], v[126:127], v[226:227]
	s_waitcnt lgkmcnt(3)
	v_pk_add_f32 v[124:125], v[124:125], v[222:223]
	v_pk_add_f32 v[122:123], v[122:123], v[218:219]
	v_pk_add_f32 v[120:121], v[120:121], v[206:207]
	v_pk_add_f32 v[118:119], v[118:119], v[172:173]
	v_pk_add_f32 v[116:117], v[116:117], v[168:169]
	v_pk_add_f32 v[114:115], v[114:115], v[164:165]
	v_pk_add_f32 v[112:113], v[112:113], v[160:161]
	s_waitcnt lgkmcnt(1)
	v_pk_add_f32 v[94:95], v[94:95], v[228:229]
	s_waitcnt lgkmcnt(0)
	v_pk_add_f32 v[92:93], v[92:93], v[224:225]
	v_pk_add_f32 v[90:91], v[90:91], v[220:221]
	v_pk_add_f32 v[88:89], v[88:89], v[208:209]
	v_pk_add_f32 v[86:87], v[86:87], v[174:175]
	v_pk_add_f32 v[84:85], v[84:85], v[170:171]
	v_pk_add_f32 v[82:83], v[82:83], v[166:167]
	v_pk_add_f32 v[80:81], v[80:81], v[162:163]
.LBB0_179:
	v_add_u32_e32 v217, s68, v199
	ds_read_b64_tr_b16 v[160:161], v217 offset:0
	ds_read_b64_tr_b16 v[162:163], v217 offset:0x800
	ds_read_b64_tr_b16 v[164:165], v217 offset:0x1000
	ds_read_b64_tr_b16 v[166:167], v217 offset:0x1800
	ds_read_b64_tr_b16 v[168:169], v217 offset:0x2000
	ds_read_b64_tr_b16 v[170:171], v217 offset:0x2800
	ds_read_b64_tr_b16 v[172:173], v217 offset:0x3000
	ds_read_b64_tr_b16 v[174:175], v217 offset:0x3800
	ds_read_b64_tr_b16 v[218:219], v217 offset:0x200
	ds_read_b64_tr_b16 v[220:221], v217 offset:0xa00
	ds_read_b64_tr_b16 v[222:223], v217 offset:0x1200
	ds_read_b64_tr_b16 v[224:225], v217 offset:0x1a00
	ds_read_b64_tr_b16 v[226:227], v217 offset:0x2200
	ds_read_b64_tr_b16 v[228:229], v217 offset:0x2a00
	ds_read_b64_tr_b16 v[230:231], v217 offset:0x3200
	ds_read_b64_tr_b16 v[232:233], v217 offset:0x3a00
	s_waitcnt lgkmcnt(8)
	s_nop 0
	v_mfma_f32_32x32x16_bf16 v[0:15], v[104:107], v[160:163], v[0:15]
	v_max3_f32 v160, v112, v113, v80
	v_max3_f32 v161, v114, v115, v81
	v_max3_f32 v160, v160, v82, v83
	v_max3_f32 v161, v161, v118, v119
	v_max3_f32 v160, v160, v116, v117
	v_mfma_f32_32x32x16_bf16 v[0:15], v[108:111], v[164:167], v[0:15]
	v_max3_f32 v160, v160, v84, v85
	v_max3_f32 v161, v161, v86, v87
	v_max3_f32 v160, v160, v120, v121
	v_max3_f32 v161, v161, v122, v123
	v_max3_f32 v160, v160, v88, v89
	v_mfma_f32_32x32x16_bf16 v[0:15], v[96:99], v[168:171], v[0:15]
	v_max3_f32 v161, v161, v90, v91
	v_max3_f32 v160, v160, v124, v125
	v_max3_f32 v161, v161, v126, v127
	v_max3_f32 v160, v160, v92, v93
	v_max3_f32 v161, v161, v94, v95
	v_mfma_f32_32x32x16_bf16 v[0:15], v[100:103], v[172:175], v[0:15]
	v_max3_f32 v206, v160, v161, v161
	ds_read_b64_tr_b16 v[172:173], v217 offset:0x400
	ds_read_b64_tr_b16 v[174:175], v217 offset:0xc00
	ds_read_b64_tr_b16 v[168:169], v217 offset:0x1400
	ds_read_b64_tr_b16 v[170:171], v217 offset:0x1c00
	ds_read_b64_tr_b16 v[164:165], v217 offset:0x2400
	ds_read_b64_tr_b16 v[166:167], v217 offset:0x2c00
	ds_read_b64_tr_b16 v[160:161], v217 offset:0x3400
	ds_read_b64_tr_b16 v[162:163], v217 offset:0x3c00
	s_waitcnt lgkmcnt(8)
	v_mfma_f32_32x32x16_bf16 v[48:63], v[104:107], v[218:221], v[48:63]
	v_mov_b32_e32 v207, v206
	s_nop 1
	v_permlane32_swap_b32_e32 v206, v207
	v_max_f32_e32 v212, v206, v207
	v_cmp_ge_f32_e32 vcc, s76, v212
	v_mfma_f32_32x32x16_bf16 v[48:63], v[108:111], v[222:225], v[48:63]
	s_cmp_eq_u64 vcc, exec
	v_mfma_f32_32x32x16_bf16 v[48:63], v[96:99], v[226:229], v[48:63]
	v_mfma_f32_32x32x16_bf16 v[48:63], v[100:103], v[230:233], v[48:63]
	s_cbranch_scc0 .LBB0_188
	v_mov_b32_e32 v212, 1.0
	s_mov_b64 vcc, 0
; #define SBAR() __builtin_amdgcn_sched_barrier(0)
; #define VRD8(D0, L0, H0, L1, H1, L2, H2, L3, H3) do { L0 = tr_read<v_rd_off(D0, 0, 0)>(vb); H0 = tr_read<v_rd_off(D0, 0, 1)>(vb); L1 = tr_read<v_rd_off(D0, 1, 0)>(vb); H1 = tr_read<v_rd_off(D0, 1, 1)>(vb); \
;     L2 = tr_read<v_rd_off(D0, 2, 0)>(vb); H2 = tr_read<v_rd_off(D0, 2, 1)>(vb); L3 = tr_read<v_rd_off(D0, 3, 0)>(vb); H3 = tr_read<v_rd_off(D0, 3, 1)>(vb); } while (0)
; #define MMA4(OD, L0, H0, L1, H1, L2, H2, L3, H3) do { OD = __builtin_amdgcn_mfma_f32_32x32x16_bf16(pa0, PK(L0, H0), OD, 0, 0, 0); OD = __builtin_amdgcn_mfma_f32_32x32x16_bf16(pa1, PK(L1, H1), OD, 0, 0, 0); \
;     OD = __builtin_amdgcn_mfma_f32_32x32x16_bf16(pa2, PK(L2, H2), OD, 0, 0, 0); OD = __builtin_amdgcn_mfma_f32_32x32x16_bf16(pa3, PK(L3, H3), OD, 0, 0, 0); } while (0)
; __device__ __forceinline__ void pv_partial(f32x16* o, int vb, bf16x8 pa0, bf16x8 pa1, bf16x8 pa2, bf16x8 pa3, f32x16& p0, f32x16& p1, float& m_ref, f32x16& negm, float& alpha) {
;     ...
;   VRD8(3, b0, b1, b2, b3, b4, b5, b6, b7);
;   asm volatile("s_waitcnt lgkmcnt(8)" ::: "memory"); SBAR();
;   MMA4(o[2], a0, a1, a2, a3, a4, a5, a6, a7);
; #pragma unroll
;   for (int r = 0; r < 8; ++r) p0[r] = __builtin_amdgcn_exp2f(p0[r]);
;   SBAR();
;   asm volatile("s_waitcnt lgkmcnt(0)" ::: "memory"); SBAR();
;   MMA4(o[3], b0, b1, b2, b3, b4, b5, b6, b7);
; #pragma unroll
;   for (int r = 8; r < 16; ++r) p0[r] = __builtin_amdgcn_exp2f(p0[r]);
.LBB0_181:
	ds_read_b64_tr_b16 v[218:219], v217 offset:0x600
	ds_read_b64_tr_b16 v[220:221], v217 offset:0xe00
	ds_read_b64_tr_b16 v[222:223], v217 offset:0x1600
	ds_read_b64_tr_b16 v[224:225], v217 offset:0x1e00
	ds_read_b64_tr_b16 v[226:227], v217 offset:0x2600
	ds_read_b64_tr_b16 v[228:229], v217 offset:0x2e00
	ds_read_b64_tr_b16 v[230:231], v217 offset:0x3600
	ds_read_b64_tr_b16 v[232:233], v217 offset:0x3e00
	s_waitcnt lgkmcnt(8)
	v_mfma_f32_32x32x16_bf16 v[32:47], v[104:107], v[172:175], v[32:47]
	v_mfma_f32_32x32x16_bf16 v[32:47], v[108:111], v[168:171], v[32:47]
	v_mfma_f32_32x32x16_bf16 v[32:47], v[96:99], v[164:167], v[32:47]
	v_mfma_f32_32x32x16_bf16 v[32:47], v[100:103], v[160:163], v[32:47]
	s_waitcnt lgkmcnt(0)
	v_mfma_f32_32x32x16_bf16 v[16:31], v[104:107], v[218:221], v[16:31]
	s_add_i32 s78, s43, 0
	v_mfma_f32_32x32x16_bf16 v[16:31], v[108:111], v[222:225], v[16:31]
	v_mfma_f32_32x32x16_bf16 v[16:31], v[96:99], v[226:229], v[16:31]
	v_mfma_f32_32x32x16_bf16 v[16:31], v[100:103], v[230:233], v[16:31]
	s_cbranch_vccz .LBB0_185
	s_and_saveexec_b64 s[10:11], s[0:1]
	ds_write_b32 v186, v212 offset:128
	s_or_b64 exec, exec, s[10:11]
	s_waitcnt lgkmcnt(0)
	v_add_u32_e32 v108, s49, v204
	ds_read_b128 v[96:99], v108 offset:224
	ds_read_b128 v[100:103], v108 offset:192
	ds_read_b128 v[104:107], v108 offset:160
	ds_read_b128 v[108:111], v108 offset:128
	s_waitcnt lgkmcnt(3)
	v_pk_mul_f32 v[12:13], v[12:13], v[96:97]
	s_waitcnt lgkmcnt(2)
	v_pk_mul_f32 v[8:9], v[8:9], v[100:101]
	s_waitcnt lgkmcnt(1)
	v_pk_mul_f32 v[4:5], v[4:5], v[104:105]
	v_pk_mul_f32 v[14:15], v[14:15], v[98:99]
	v_pk_mul_f32 v[10:11], v[10:11], v[102:103]
	v_pk_mul_f32 v[6:7], v[6:7], v[106:107]
	s_waitcnt lgkmcnt(0)
	v_pk_mul_f32 v[2:3], v[2:3], v[110:111]
	v_pk_mul_f32 v[0:1], v[0:1], v[108:109]
	v_pk_mul_f32 v[60:61], v[60:61], v[96:97]
	v_pk_mul_f32 v[56:57], v[56:57], v[100:101]
	v_pk_mul_f32 v[52:53], v[52:53], v[104:105]
	v_pk_mul_f32 v[62:63], v[62:63], v[98:99]
	v_pk_mul_f32 v[58:59], v[58:59], v[102:103]
	v_pk_mul_f32 v[54:55], v[54:55], v[106:107]
	v_pk_mul_f32 v[50:51], v[50:51], v[110:111]
	v_pk_mul_f32 v[48:49], v[48:49], v[108:109]
	v_pk_mul_f32 v[44:45], v[44:45], v[96:97]
	v_pk_mul_f32 v[40:41], v[40:41], v[100:101]
	v_pk_mul_f32 v[36:37], v[36:37], v[104:105]
	v_pk_mul_f32 v[46:47], v[46:47], v[98:99]
	v_pk_mul_f32 v[42:43], v[42:43], v[102:103]
	v_pk_mul_f32 v[38:39], v[38:39], v[106:107]
	v_pk_mul_f32 v[34:35], v[34:35], v[110:111]
	v_pk_mul_f32 v[32:33], v[32:33], v[108:109]
	v_pk_mul_f32 v[28:29], v[28:29], v[96:97]
	v_pk_mul_f32 v[24:25], v[24:25], v[100:101]
	v_pk_mul_f32 v[20:21], v[20:21], v[104:105]
	v_pk_mul_f32 v[30:31], v[30:31], v[98:99]
	v_pk_mul_f32 v[26:27], v[26:27], v[102:103]
	v_pk_mul_f32 v[22:23], v[22:23], v[106:107]
	v_pk_mul_f32 v[18:19], v[18:19], v[110:111]
	v_pk_mul_f32 v[16:17], v[16:17], v[108:109]
.LBB0_185:
	v_exp_f32_e32 v173, v112
	v_exp_f32_e32 v175, v113
	v_exp_f32_e32 v171, v114
	v_exp_f32_e32 v174, v115
	v_exp_f32_e32 v169, v116
	v_exp_f32_e32 v172, v117
	v_exp_f32_e32 v168, v118
	v_exp_f32_e32 v170, v119
	v_exp_f32_e32 v165, v120
	v_exp_f32_e32 v167, v121
	v_exp_f32_e32 v163, v122
	v_exp_f32_e32 v166, v123
	v_exp_f32_e32 v161, v124
	v_exp_f32_e32 v164, v125
	v_exp_f32_e32 v160, v126
	v_exp_f32_e32 v162, v127
	v_fma_f32 v96, v203, v187, v210
	s_add_i32 s57, s57, 2
	s_mov_b64 s[10:11], 0x120000
	v_fma_f32 v187, v96, v213, v215
	s_cmp_ge_u32 s57, s67
	v_lshl_add_u64 v[176:177], v[176:177], 0, s[10:11]
	s_waitcnt vmcnt(0)
	s_waitcnt lgkmcnt(0)
	s_barrier
	s_cbranch_scc1 .LBB0_189
	s_mov_b32 s10, s18
	s_mov_b32 s18, s68
	v_mov_b32_e32 v203, v212
	s_branch .LBB0_163
; __device__ __forceinline__ void pv_partial(f32x16* o, int vb, bf16x8 pa0, bf16x8 pa1, bf16x8 pa2, bf16x8 pa3, f32x16& p0, f32x16& p1, float& m_ref, f32x16& negm, float& alpha) {
;     ...
;   { auto rr = __builtin_amdgcn_permlane32_swap(__float_as_uint(pmax), __float_as_uint(pmax), false, false);
;     pmax = fmaxf(__uint_as_float(rr[0]), __uint_as_float(rr[1])); }
;   alpha = 1.f;
;   if (!__builtin_expect(__all(pmax <= THR), 1)) {
;     const float dl = fmaxf(pmax, 0.f); m_ref += dl; alpha = __builtin_amdgcn_exp2f(-dl);
; #pragma unroll
;     for (int r = 0; r < 16; ++r) { p0[r] -= dl; p1[r] -= dl; negm[r] -= dl; }
;   }
.LBB0_187:
	v_max_f32_e32 v206, v213, v213
	v_max_f32_e32 v206, 0, v206
	v_exp_f32_e64 v213, -v206
	v_pk_add_f32 v[112:113], v[112:113], v[206:207] op_sel_hi:[1,0] neg_lo:[0,1] neg_hi:[0,1]
	v_pk_add_f32 v[114:115], v[114:115], v[206:207] op_sel_hi:[1,0] neg_lo:[0,1] neg_hi:[0,1]
	v_pk_add_f32 v[116:117], v[116:117], v[206:207] op_sel_hi:[1,0] neg_lo:[0,1] neg_hi:[0,1]
	v_pk_add_f32 v[118:119], v[118:119], v[206:207] op_sel_hi:[1,0] neg_lo:[0,1] neg_hi:[0,1]
	v_pk_add_f32 v[120:121], v[120:121], v[206:207] op_sel_hi:[1,0] neg_lo:[0,1] neg_hi:[0,1]
	v_pk_add_f32 v[122:123], v[122:123], v[206:207] op_sel_hi:[1,0] neg_lo:[0,1] neg_hi:[0,1]
	v_pk_add_f32 v[124:125], v[124:125], v[206:207] op_sel_hi:[1,0] neg_lo:[0,1] neg_hi:[0,1]
	v_pk_add_f32 v[126:127], v[126:127], v[206:207] op_sel_hi:[1,0] neg_lo:[0,1] neg_hi:[0,1]
	v_sub_f32_e32 v111, v111, v206
	v_sub_f32_e32 v110, v110, v206
	v_sub_f32_e32 v109, v109, v206
	v_sub_f32_e32 v108, v108, v206
	v_sub_f32_e32 v107, v107, v206
	v_sub_f32_e32 v106, v106, v206
	v_sub_f32_e32 v105, v105, v206
	v_sub_f32_e32 v104, v104, v206
	v_sub_f32_e32 v103, v103, v206
	v_sub_f32_e32 v102, v102, v206
	v_sub_f32_e32 v101, v101, v206
	v_sub_f32_e32 v100, v100, v206
	v_sub_f32_e32 v99, v99, v206
	v_sub_f32_e32 v98, v98, v206
	v_sub_f32_e32 v97, v97, v206
	v_sub_f32_e32 v96, v96, v206
	v_sub_f32_e32 v79, v79, v206
	v_sub_f32_e32 v78, v78, v206
	v_sub_f32_e32 v77, v77, v206
	v_sub_f32_e32 v76, v76, v206
	v_sub_f32_e32 v75, v75, v206
	v_sub_f32_e32 v74, v74, v206
	v_sub_f32_e32 v73, v73, v206
	v_sub_f32_e32 v72, v72, v206
	v_sub_f32_e32 v71, v71, v206
	v_sub_f32_e32 v70, v70, v206
	v_sub_f32_e32 v69, v69, v206
	v_sub_f32_e32 v68, v68, v206
	v_sub_f32_e32 v67, v67, v206
	v_sub_f32_e32 v66, v66, v206
	v_sub_f32_e32 v65, v65, v206
	v_sub_f32_e32 v64, v64, v206
	v_cmp_gt_f32_e32 vcc, 1.0, v213
	s_branch .LBB0_170
.LBB0_188:
	v_max_f32_e32 v206, v212, v212
	v_max_f32_e32 v206, 0, v206
	v_exp_f32_e64 v212, -v206
	v_pk_add_f32 v[112:113], v[112:113], v[206:207] op_sel_hi:[1,0] neg_lo:[0,1] neg_hi:[0,1]
	v_pk_add_f32 v[114:115], v[114:115], v[206:207] op_sel_hi:[1,0] neg_lo:[0,1] neg_hi:[0,1]
	v_pk_add_f32 v[116:117], v[116:117], v[206:207] op_sel_hi:[1,0] neg_lo:[0,1] neg_hi:[0,1]
	v_pk_add_f32 v[118:119], v[118:119], v[206:207] op_sel_hi:[1,0] neg_lo:[0,1] neg_hi:[0,1]
	v_pk_add_f32 v[120:121], v[120:121], v[206:207] op_sel_hi:[1,0] neg_lo:[0,1] neg_hi:[0,1]
	v_pk_add_f32 v[122:123], v[122:123], v[206:207] op_sel_hi:[1,0] neg_lo:[0,1] neg_hi:[0,1]
	v_pk_add_f32 v[124:125], v[124:125], v[206:207] op_sel_hi:[1,0] neg_lo:[0,1] neg_hi:[0,1]
	v_pk_add_f32 v[126:127], v[126:127], v[206:207] op_sel_hi:[1,0] neg_lo:[0,1] neg_hi:[0,1]
	v_sub_f32_e32 v95, v95, v206
	v_sub_f32_e32 v94, v94, v206
	v_sub_f32_e32 v93, v93, v206
	v_sub_f32_e32 v92, v92, v206
	v_sub_f32_e32 v91, v91, v206
	v_sub_f32_e32 v90, v90, v206
	v_sub_f32_e32 v89, v89, v206
	v_sub_f32_e32 v88, v88, v206
	v_sub_f32_e32 v87, v87, v206
	v_sub_f32_e32 v86, v86, v206
	v_sub_f32_e32 v85, v85, v206
	v_sub_f32_e32 v84, v84, v206
	v_sub_f32_e32 v83, v83, v206
	v_sub_f32_e32 v82, v82, v206
	v_sub_f32_e32 v81, v81, v206
	v_sub_f32_e32 v80, v80, v206
	v_sub_f32_e32 v79, v79, v206
	v_sub_f32_e32 v78, v78, v206
	v_sub_f32_e32 v77, v77, v206
	v_sub_f32_e32 v76, v76, v206
	v_sub_f32_e32 v75, v75, v206
	v_sub_f32_e32 v74, v74, v206
	v_sub_f32_e32 v73, v73, v206
	v_sub_f32_e32 v72, v72, v206
	v_sub_f32_e32 v71, v71, v206
	v_sub_f32_e32 v70, v70, v206
	v_sub_f32_e32 v69, v69, v206
	v_sub_f32_e32 v68, v68, v206
	v_sub_f32_e32 v67, v67, v206
	v_sub_f32_e32 v66, v66, v206
	v_sub_f32_e32 v65, v65, v206
	v_sub_f32_e32 v64, v64, v206
	v_cmp_gt_f32_e32 vcc, 1.0, v212
	s_branch .LBB0_181

; #define SBAR() __builtin_amdgcn_sched_barrier(0)
; #define VRD8(D0, L0, H0, L1, H1, L2, H2, L3, H3) do { L0 = tr_read<v_rd_off(D0, 0, 0)>(vb); H0 = tr_read<v_rd_off(D0, 0, 1)>(vb); L1 = tr_read<v_rd_off(D0, 1, 0)>(vb); H1 = tr_read<v_rd_off(D0, 1, 1)>(vb); \
;     L2 = tr_read<v_rd_off(D0, 2, 0)>(vb); H2 = tr_read<v_rd_off(D0, 2, 1)>(vb); L3 = tr_read<v_rd_off(D0, 3, 0)>(vb); H3 = tr_read<v_rd_off(D0, 3, 1)>(vb); } while (0)
; #define MMA4(OD, L0, H0, L1, H1, L2, H2, L3, H3) do { OD = __builtin_amdgcn_mfma_f32_32x32x16_bf16(pa0, PK(L0, H0), OD, 0, 0, 0); OD = __builtin_amdgcn_mfma_f32_32x32x16_bf16(pa1, PK(L1, H1), OD, 0, 0, 0); \
;     OD = __builtin_amdgcn_mfma_f32_32x32x16_bf16(pa2, PK(L2, H2), OD, 0, 0, 0); OD = __builtin_amdgcn_mfma_f32_32x32x16_bf16(pa3, PK(L3, H3), OD, 0, 0, 0); } while (0)
; __device__ __forceinline__ void finishSM(f32x16& p0, f32x16& p1, float alpha, float& l_reg, bf16x8& pa0, bf16x8& pa1, bf16x8& pa2, bf16x8& pa3) {
; #pragma unroll
;   for (int r = 0; r < 16; ++r) p1[r] = __builtin_amdgcn_exp2f(p1[r]);
;   float ps = 0;
; #pragma unroll
;   for (int r = 0; r < 16; ++r) ps += p0[r];
; #pragma unroll
;   for (int r = 0; r < 16; ++r) ps += p1[r];
;   { auto rr = __builtin_amdgcn_permlane32_swap(__float_as_uint(ps), __float_as_uint(ps), false, false);
;     ps = __uint_as_float(rr[0]) + __uint_as_float(rr[1]); }
;   l_reg = l_reg * alpha + ps;
;     ...
;   PK4(p0, 0, pa0); PK4(p0, 8, pa1); PK4(p1, 0, pa2); PK4(p1, 8, pa3);
; __device__ __forceinline__ void pv_d0(f32x16* o, int vb, bf16x8 pa0, bf16x8 pa1, bf16x8 pa2, bf16x8 pa3) {
;   s16x4 a0, a1, a2, a3, a4, a5, a6, a7, b0, b1, b2, b3, b4, b5, b6, b7;
;   VRD8(0, a0, a1, a2, a3, a4, a5, a6, a7);
;   VRD8(1, b0, b1, b2, b3, b4, b5, b6, b7);
;   asm volatile("s_waitcnt lgkmcnt(8)" ::: "memory"); SBAR();
;   MMA4(o[0], a0, a1, a2, a3, a4, a5, a6, a7); SBAR();
;   VRD8(2, a0, a1, a2, a3, a4, a5, a6, a7);
;   asm volatile("s_waitcnt lgkmcnt(8)" ::: "memory"); SBAR();
;   MMA4(o[1], b0, b1, b2, b3, b4, b5, b6, b7); SBAR();
;   VRD8(3, b0, b1, b2, b3, b4, b5, b6, b7);
;   asm volatile("s_waitcnt lgkmcnt(8)" ::: "memory"); SBAR();
;   MMA4(o[2], a0, a1, a2, a3, a4, a5, a6, a7); SBAR();
;   asm volatile("s_waitcnt lgkmcnt(0)" ::: "memory"); SBAR();
;   MMA4(o[3], b0, b1, b2, b3, b4, b5, b6, b7);
; }
.LBB0_199:
	v_exp_f32_e32 v80, v96
	v_exp_f32_e32 v81, v97
	v_exp_f32_e32 v82, v98
	v_exp_f32_e32 v83, v99
	v_exp_f32_e32 v84, v100
	v_exp_f32_e32 v96, v64
	v_add_f32_e32 v64, 0, v80
	v_exp_f32_e32 v85, v101
	v_add_f32_e32 v64, v81, v64
	v_exp_f32_e32 v86, v102
	v_add_f32_e32 v64, v82, v64
	v_exp_f32_e32 v87, v103
	v_add_f32_e32 v64, v83, v64
	v_exp_f32_e32 v88, v104
	v_add_f32_e32 v64, v84, v64
	v_exp_f32_e32 v89, v105
	v_add_f32_e32 v64, v85, v64
	v_exp_f32_e32 v90, v106
	v_add_f32_e32 v64, v86, v64
	v_exp_f32_e32 v91, v107
	v_add_f32_e32 v64, v87, v64
	v_exp_f32_e32 v92, v108
	v_add_f32_e32 v64, v88, v64
	v_exp_f32_e32 v93, v109
	v_add_f32_e32 v64, v89, v64
	v_exp_f32_e32 v94, v110
	v_add_f32_e32 v64, v90, v64
	v_exp_f32_e32 v95, v111
	v_add_f32_e32 v64, v91, v64
	v_add_f32_e32 v64, v92, v64
	v_exp_f32_e32 v97, v65
	v_add_f32_e32 v64, v93, v64
	v_exp_f32_e32 v98, v66
	v_add_f32_e32 v64, v94, v64
	v_exp_f32_e32 v99, v67
	v_add_f32_e32 v64, v95, v64
	v_exp_f32_e32 v100, v68
	v_add_f32_e32 v64, v96, v64
	v_exp_f32_e32 v101, v69
	v_add_f32_e32 v64, v97, v64
	v_exp_f32_e32 v102, v70
	v_add_f32_e32 v64, v98, v64
	v_exp_f32_e32 v103, v71
	v_add_f32_e32 v64, v99, v64
	v_exp_f32_e32 v104, v72
	v_add_f32_e32 v64, v100, v64
	v_exp_f32_e32 v105, v73
	v_add_f32_e32 v64, v101, v64
	v_exp_f32_e32 v106, v74
	v_add_f32_e32 v64, v102, v64
	v_exp_f32_e32 v107, v75
	v_add_f32_e32 v64, v103, v64
	v_exp_f32_e32 v108, v76
	v_add_f32_e32 v64, v104, v64
	v_exp_f32_e32 v109, v77
	v_add_f32_e32 v64, v105, v64
	v_exp_f32_e32 v110, v78
	v_add_f32_e32 v64, v106, v64
	v_exp_f32_e32 v111, v79
	v_add_f32_e32 v64, v107, v64
	v_add_f32_e32 v64, v108, v64
	v_add_f32_e32 v64, v109, v64
	v_add_f32_e32 v64, v110, v64
	v_add_f32_e32 v64, v111, v64
	v_mov_b32_e32 v65, v64
	s_nop 1
	v_permlane32_swap_b32_e32 v64, v65
	v_cvt_pk_bf16_f32 v66, v80, v81
	v_cvt_pk_bf16_f32 v67, v82, v83
	v_cvt_pk_bf16_f32 v68, v84, v85
	v_cvt_pk_bf16_f32 v69, v86, v87
	v_cvt_pk_bf16_f32 v70, v88, v89
	v_cvt_pk_bf16_f32 v71, v90, v91
	v_cvt_pk_bf16_f32 v72, v92, v93
	v_cvt_pk_bf16_f32 v73, v94, v95
	v_cvt_pk_bf16_f32 v74, v96, v97
	v_cvt_pk_bf16_f32 v75, v98, v99
	v_cvt_pk_bf16_f32 v76, v100, v101
	v_cvt_pk_bf16_f32 v77, v102, v103
	v_cvt_pk_bf16_f32 v78, v104, v105
	v_cvt_pk_bf16_f32 v79, v106, v107
	v_cvt_pk_bf16_f32 v80, v108, v109
	v_cvt_pk_bf16_f32 v81, v110, v111
	s_nop 0
	ds_read_b64_tr_b16 v[82:83], v201 offset:0
	ds_read_b64_tr_b16 v[84:85], v201 offset:0x800
	ds_read_b64_tr_b16 v[86:87], v201 offset:0x1000
	ds_read_b64_tr_b16 v[88:89], v201 offset:0x1800
	ds_read_b64_tr_b16 v[90:91], v201 offset:0x2000
	ds_read_b64_tr_b16 v[92:93], v201 offset:0x2800
	ds_read_b64_tr_b16 v[94:95], v201 offset:0x3000
	ds_read_b64_tr_b16 v[96:97], v201 offset:0x3800
	ds_read_b64_tr_b16 v[98:99], v201 offset:0x200
	ds_read_b64_tr_b16 v[100:101], v201 offset:0xa00
	ds_read_b64_tr_b16 v[102:103], v201 offset:0x1200
	ds_read_b64_tr_b16 v[104:105], v201 offset:0x1a00
	ds_read_b64_tr_b16 v[106:107], v201 offset:0x2200
	ds_read_b64_tr_b16 v[108:109], v201 offset:0x2a00
	ds_read_b64_tr_b16 v[110:111], v201 offset:0x3200
	ds_read_b64_tr_b16 v[112:113], v201 offset:0x3a00
	s_waitcnt lgkmcnt(8)
	s_nop 0
	v_mfma_f32_32x32x16_bf16 v[0:15], v[66:69], v[82:85], v[0:15]
	v_mfma_f32_32x32x16_bf16 v[0:15], v[70:73], v[86:89], v[0:15]
	v_mfma_f32_32x32x16_bf16 v[0:15], v[74:77], v[90:93], v[0:15]
	v_mfma_f32_32x32x16_bf16 v[0:15], v[78:81], v[94:97], v[0:15]
	ds_read_b64_tr_b16 v[82:83], v201 offset:0x400
	ds_read_b64_tr_b16 v[84:85], v201 offset:0xc00
	ds_read_b64_tr_b16 v[86:87], v201 offset:0x1400
	ds_read_b64_tr_b16 v[88:89], v201 offset:0x1c00
	ds_read_b64_tr_b16 v[90:91], v201 offset:0x2400
	ds_read_b64_tr_b16 v[92:93], v201 offset:0x2c00
	ds_read_b64_tr_b16 v[94:95], v201 offset:0x3400
	ds_read_b64_tr_b16 v[96:97], v201 offset:0x3c00
	s_waitcnt lgkmcnt(8)
	v_mfma_f32_32x32x16_bf16 v[48:63], v[66:69], v[98:101], v[48:63]
	v_mfma_f32_32x32x16_bf16 v[48:63], v[70:73], v[102:105], v[48:63]
	v_mfma_f32_32x32x16_bf16 v[48:63], v[74:77], v[106:109], v[48:63]
	v_mfma_f32_32x32x16_bf16 v[48:63], v[78:81], v[110:113], v[48:63]
	ds_read_b64_tr_b16 v[98:99], v201 offset:0x600
	ds_read_b64_tr_b16 v[100:101], v201 offset:0xe00
	ds_read_b64_tr_b16 v[102:103], v201 offset:0x1600
	ds_read_b64_tr_b16 v[104:105], v201 offset:0x1e00
	ds_read_b64_tr_b16 v[106:107], v201 offset:0x2600
	ds_read_b64_tr_b16 v[108:109], v201 offset:0x2e00
	ds_read_b64_tr_b16 v[110:111], v201 offset:0x3600
	ds_read_b64_tr_b16 v[112:113], v201 offset:0x3e00
	s_waitcnt lgkmcnt(8)
	v_mfma_f32_32x32x16_bf16 v[32:47], v[66:69], v[82:85], v[32:47]
	v_mfma_f32_32x32x16_bf16 v[32:47], v[70:73], v[86:89], v[32:47]
	v_mfma_f32_32x32x16_bf16 v[32:47], v[74:77], v[90:93], v[32:47]
	v_mfma_f32_32x32x16_bf16 v[32:47], v[78:81], v[94:97], v[32:47]
	s_waitcnt lgkmcnt(0)
	v_mfma_f32_32x32x16_bf16 v[16:31], v[66:69], v[98:101], v[16:31]
	v_mfma_f32_32x32x16_bf16 v[16:31], v[70:73], v[102:105], v[16:31]
	v_mfma_f32_32x32x16_bf16 v[16:31], v[74:77], v[106:109], v[16:31]
	v_mfma_f32_32x32x16_bf16 v[16:31], v[78:81], v[110:113], v[16:31]
	v_mov_b32_e32 v252, v187
	s_nop 1
	v_permlane32_swap_b32_e32 v187, v252
	s_nop 1
	v_add_f32_e32 v187, v187, v252
	s_and_saveexec_b64 s[10:11], s[0:1]
	v_add_f32_e32 v66, v128, v129
	v_fmac_f32_e32 v66, v187, v212
	v_add_f32_e32 v64, v64, v65
	v_fmac_f32_e32 v64, v66, v130
	ds_write_b32 v186, v64
	s_or_b64 exec, exec, s[10:11]
	s_waitcnt lgkmcnt(0)
	v_add_u32_e32 v64, s49, v204
	ds_read_b128 v[66:69], v64
	ds_read_b128 v[76:79], v64 offset:32
	s_lshl_b32 s0, s66, 14
	s_add_i32 s0, s0, 0
	ds_read_b128 v[84:87], v64 offset:96
	s_waitcnt lgkmcnt(2)
	v_rcp_f32_e32 v73, v68
	v_rcp_f32_e32 v74, v69
	ds_read_b128 v[68:71], v64 offset:64
	v_rcp_f32_e32 v66, v66
	v_rcp_f32_e32 v72, v67
	s_waitcnt lgkmcnt(2)
	v_rcp_f32_e32 v75, v76
	v_rcp_f32_e32 v77, v77
	v_rcp_f32_e32 v78, v78
	v_rcp_f32_e32 v80, v79
	s_waitcnt lgkmcnt(0)
	v_rcp_f32_e32 v81, v68
	v_rcp_f32_e32 v83, v69
	v_rcp_f32_e32 v82, v70
	v_rcp_f32_e32 v79, v71
	v_rcp_f32_e32 v76, v84
	v_rcp_f32_e32 v71, v85
	v_rcp_f32_e32 v68, v86
	v_rcp_f32_e32 v69, v87
	v_lshlrev_b32_e32 v64, 11, v185
	v_lshlrev_b32_e32 v67, 2, v184
	s_cmp_lg_u32 s64, 1
	v_add3_u32 v70, s0, v64, v67
	s_barrier
; __device__ __forceinline__ int crow(int r, int hi) { return (r & 3) + 8 * (r >> 2) + 4 * hi; }
; template <int MODE, int ORD> ...
;     ...
;     float* X = (float*)lds + wq * 4096;
;     if (cst == 1) {
; #pragma unroll
;       for (int r = 0; r < 16; ++r) { const int orow = crow(r, hi);
; #pragma unroll
;         for (int d0 = 0; d0 < 4; ++d0) X[orow * 128 + d0 * 32 + r32] = o[d0][r] * rli[r]; }
;     }
	s_cbranch_scc1 .LBB0_203
	v_mul_f32_e32 v64, v0, v66
	v_mul_f32_e32 v65, v48, v66
	ds_write2_b32 v70, v64, v65 offset1:32
	v_mul_f32_e32 v64, v32, v66
	v_mul_f32_e32 v65, v16, v66
	ds_write2_b32 v70, v64, v65 offset0:64 offset1:96
	v_mul_f32_e32 v64, v1, v72
	v_mul_f32_e32 v65, v49, v72
	ds_write2_b32 v70, v64, v65 offset0:128 offset1:160
	v_mul_f32_e32 v64, v33, v72
	v_mul_f32_e32 v65, v17, v72
	ds_write2_b32 v70, v64, v65 offset0:192 offset1:224
	v_mul_f32_e32 v64, v2, v73
	v_mul_f32_e32 v65, v50, v73
	v_add_u32_e32 v84, 0x400, v70
	ds_write2_b32 v84, v64, v65 offset1:32
	v_mul_f32_e32 v64, v34, v73
	v_mul_f32_e32 v65, v18, v73
	ds_write2_b32 v84, v64, v65 offset0:64 offset1:96
	v_mul_f32_e32 v64, v3, v74
	v_mul_f32_e32 v65, v51, v74
	ds_write2_b32 v84, v64, v65 offset0:128 offset1:160
	v_mul_f32_e32 v64, v35, v74
	v_mul_f32_e32 v65, v19, v74
	ds_write2_b32 v84, v64, v65 offset0:192 offset1:224
	v_mul_f32_e32 v64, v4, v75
	v_mul_f32_e32 v65, v52, v75
	v_add_u32_e32 v84, 0x1000, v70
	ds_write2_b32 v84, v64, v65 offset1:32
	v_mul_f32_e32 v64, v36, v75
	v_mul_f32_e32 v65, v20, v75
	ds_write2_b32 v84, v64, v65 offset0:64 offset1:96
	v_mul_f32_e32 v64, v5, v77
	v_mul_f32_e32 v65, v53, v77
	ds_write2_b32 v84, v64, v65 offset0:128 offset1:160
	v_mul_f32_e32 v64, v37, v77
	v_mul_f32_e32 v65, v21, v77
	ds_write2_b32 v84, v64, v65 offset0:192 offset1:224
	v_mul_f32_e32 v64, v6, v78
	v_mul_f32_e32 v65, v54, v78
	v_add_u32_e32 v84, 0x1400, v70
	ds_write2_b32 v84, v64, v65 offset1:32
	v_mul_f32_e32 v64, v38, v78
	v_mul_f32_e32 v65, v22, v78
	ds_write2_b32 v84, v64, v65 offset0:64 offset1:96
	v_mul_f32_e32 v64, v7, v80
	v_mul_f32_e32 v65, v55, v80
	ds_write2_b32 v84, v64, v65 offset0:128 offset1:160
	v_mul_f32_e32 v64, v39, v80
	v_mul_f32_e32 v65, v23, v80
	ds_write2_b32 v84, v64, v65 offset0:192 offset1:224
	v_mul_f32_e32 v64, v8, v81
	v_mul_f32_e32 v65, v56, v81
	v_add_u32_e32 v84, 0x2000, v70
	ds_write2_b32 v84, v64, v65 offset1:32
	v_mul_f32_e32 v64, v40, v81
	v_mul_f32_e32 v65, v24, v81
	ds_write2_b32 v84, v64, v65 offset0:64 offset1:96
	v_mul_f32_e32 v64, v9, v83
	v_mul_f32_e32 v65, v57, v83
	ds_write2_b32 v84, v64, v65 offset0:128 offset1:160
	v_mul_f32_e32 v64, v41, v83
	v_mul_f32_e32 v65, v25, v83
	ds_write2_b32 v84, v64, v65 offset0:192 offset1:224
	v_mul_f32_e32 v64, v10, v82
	v_mul_f32_e32 v65, v58, v82
	v_add_u32_e32 v84, 0x2400, v70
	ds_write2_b32 v84, v64, v65 offset1:32
	v_mul_f32_e32 v64, v42, v82
	v_mul_f32_e32 v65, v26, v82
	ds_write2_b32 v84, v64, v65 offset0:64 offset1:96
	v_mul_f32_e32 v64, v11, v79
	v_mul_f32_e32 v65, v59, v79
	ds_write2_b32 v84, v64, v65 offset0:128 offset1:160
	v_mul_f32_e32 v64, v43, v79
	v_mul_f32_e32 v65, v27, v79
	ds_write2_b32 v84, v64, v65 offset0:192 offset1:224
	v_mul_f32_e32 v64, v12, v76
	v_mul_f32_e32 v65, v60, v76
	v_add_u32_e32 v84, 0x3000, v70
	ds_write2_b32 v84, v64, v65 offset1:32
	v_mul_f32_e32 v64, v44, v76
	v_mul_f32_e32 v65, v28, v76
	ds_write2_b32 v84, v64, v65 offset0:64 offset1:96
	v_mul_f32_e32 v64, v13, v71
	v_mul_f32_e32 v65, v61, v71
	ds_write2_b32 v84, v64, v65 offset0:128 offset1:160
	v_mul_f32_e32 v64, v45, v71
	v_mul_f32_e32 v65, v29, v71
	ds_write2_b32 v84, v64, v65 offset0:192 offset1:224
	v_mul_f32_e32 v64, v14, v68
	v_mul_f32_e32 v65, v62, v68
	v_add_u32_e32 v84, 0x3400, v70
	ds_write2_b32 v84, v64, v65 offset1:32
	v_mul_f32_e32 v64, v46, v68
	v_mul_f32_e32 v65, v30, v68
	ds_write2_b32 v84, v64, v65 offset0:64 offset1:96
	v_mul_f32_e32 v64, v15, v69
	v_mul_f32_e32 v65, v63, v69
	ds_write2_b32 v84, v64, v65 offset0:128 offset1:160
	v_mul_f32_e32 v64, v47, v69
	v_mul_f32_e32 v65, v31, v69
	ds_write2_b32 v84, v64, v65 offset0:192 offset1:224
